# k9: rel-bias table staged to LDS once per workgroup instead of once per unit; sgemm units XCD-aware
# baseline (speedup 1.0000x reference)
.Lsg3_unit:
	s_and_b32 s28, s12, 0xff
	s_lshr_b32 s29, s12, 8
	s_and_b32 s26, s28, 7
	s_lshl_b32 s26, s26, 1
	s_lshr_b32 s28, s28, 3
	s_lshr_b32 s25, s28, 4
	s_add_u32 s26, s26, s25
	s_bfe_u32 s25, s28, 0x10003
	s_and_b32 s27, s28, 7
	s_lshl_b32 s29, s29, 3
	s_add_u32 s27, s27, s29
	s_lshl_b32 s30, s25, 10
	s_lshl_b32 s31, s27, 16
	s_add_u32 s31, s31, s30
	s_lshl_b32 s33, s26, 17
	s_add_u32 s33, s33, s30
	v_add_u32_e32 v226, s31, v232
	v_add_u32_e32 v227, s33, v232
	v_add_u32_e32 v228, 0x10000, v227
	s_lshl_b32 s34, s25, 21
	s_lshl_b32 s35, s27, 17
	s_add_u32 s34, s34, s35
	s_lshl_b32 s35, s26, 8
	s_add_u32 s34, s34, s35
	v_add_u32_e32 v229, s34, v233
	global_load_dwordx4 v[34:37], v226, s[20:21] offset:0
	global_load_dwordx4 v[50:53], v227, s[6:7] offset:0
	global_load_dwordx4 v[66:69], v228, s[6:7] offset:0
	global_load_dwordx4 v[38:41], v226, s[20:21] offset:32
	global_load_dwordx4 v[54:57], v227, s[6:7] offset:32
	global_load_dwordx4 v[70:73], v228, s[6:7] offset:32
	global_load_dwordx4 v[42:45], v226, s[20:21] offset:64
	global_load_dwordx4 v[58:61], v227, s[6:7] offset:64
	global_load_dwordx4 v[74:77], v228, s[6:7] offset:64
	global_load_dwordx4 v[46:49], v226, s[20:21] offset:96
	global_load_dwordx4 v[62:65], v227, s[6:7] offset:96
	global_load_dwordx4 v[78:81], v228, s[6:7] offset:96
	global_load_dwordx4 v[82:85], v226, s[20:21] offset:128
	global_load_dwordx4 v[98:101], v227, s[6:7] offset:128
	global_load_dwordx4 v[114:117], v228, s[6:7] offset:128
	global_load_dwordx4 v[86:89], v226, s[20:21] offset:160
	global_load_dwordx4 v[102:105], v227, s[6:7] offset:160
	global_load_dwordx4 v[118:121], v228, s[6:7] offset:160
	global_load_dwordx4 v[90:93], v226, s[20:21] offset:192
	global_load_dwordx4 v[106:109], v227, s[6:7] offset:192
	global_load_dwordx4 v[122:125], v228, s[6:7] offset:192
	global_load_dwordx4 v[94:97], v226, s[20:21] offset:224
	global_load_dwordx4 v[110:113], v227, s[6:7] offset:224
	global_load_dwordx4 v[126:129], v228, s[6:7] offset:224
	global_load_dwordx4 v[130:133], v226, s[20:21] offset:256
	global_load_dwordx4 v[146:149], v227, s[6:7] offset:256
	global_load_dwordx4 v[162:165], v228, s[6:7] offset:256
	global_load_dwordx4 v[134:137], v226, s[20:21] offset:288
	global_load_dwordx4 v[150:153], v227, s[6:7] offset:288
	global_load_dwordx4 v[166:169], v228, s[6:7] offset:288
	global_load_dwordx4 v[138:141], v226, s[20:21] offset:320
	global_load_dwordx4 v[154:157], v227, s[6:7] offset:320
	global_load_dwordx4 v[170:173], v228, s[6:7] offset:320
	global_load_dwordx4 v[142:145], v226, s[20:21] offset:352
	global_load_dwordx4 v[158:161], v227, s[6:7] offset:352
	global_load_dwordx4 v[174:177], v228, s[6:7] offset:352
	global_load_dwordx4 v[178:181], v226, s[20:21] offset:384
	global_load_dwordx4 v[194:197], v227, s[6:7] offset:384
	global_load_dwordx4 v[210:213], v228, s[6:7] offset:384
	global_load_dwordx4 v[182:185], v226, s[20:21] offset:416
	global_load_dwordx4 v[198:201], v227, s[6:7] offset:416
	global_load_dwordx4 v[214:217], v228, s[6:7] offset:416
	global_load_dwordx4 v[186:189], v226, s[20:21] offset:448
	global_load_dwordx4 v[202:205], v227, s[6:7] offset:448
	global_load_dwordx4 v[218:221], v228, s[6:7] offset:448
	global_load_dwordx4 v[190:193], v226, s[20:21] offset:480
	global_load_dwordx4 v[206:209], v227, s[6:7] offset:480
	global_load_dwordx4 v[222:225], v228, s[6:7] offset:480
	s_waitcnt vmcnt(45)
	v_mfma_f32_32x32x16_bf16 v[2:17], v[34:37], v[50:53], 0
	v_mfma_f32_32x32x16_bf16 v[18:33], v[34:37], v[66:69], 0
	s_waitcnt vmcnt(42)
	v_mfma_f32_32x32x16_bf16 v[2:17], v[38:41], v[54:57], v[2:17]
	v_mfma_f32_32x32x16_bf16 v[18:33], v[38:41], v[70:73], v[18:33]
	s_waitcnt vmcnt(39)
	v_mfma_f32_32x32x16_bf16 v[2:17], v[42:45], v[58:61], v[2:17]
	v_mfma_f32_32x32x16_bf16 v[18:33], v[42:45], v[74:77], v[18:33]
	s_waitcnt vmcnt(36)
	v_mfma_f32_32x32x16_bf16 v[2:17], v[46:49], v[62:65], v[2:17]
	v_mfma_f32_32x32x16_bf16 v[18:33], v[46:49], v[78:81], v[18:33]
	global_load_dwordx4 v[34:37], v226, s[20:21] offset:512
	global_load_dwordx4 v[50:53], v227, s[6:7] offset:512
	global_load_dwordx4 v[66:69], v228, s[6:7] offset:512
	global_load_dwordx4 v[38:41], v226, s[20:21] offset:544
	global_load_dwordx4 v[54:57], v227, s[6:7] offset:544
	global_load_dwordx4 v[70:73], v228, s[6:7] offset:544
	global_load_dwordx4 v[42:45], v226, s[20:21] offset:576
	global_load_dwordx4 v[58:61], v227, s[6:7] offset:576
	global_load_dwordx4 v[74:77], v228, s[6:7] offset:576
	global_load_dwordx4 v[46:49], v226, s[20:21] offset:608
	global_load_dwordx4 v[62:65], v227, s[6:7] offset:608
	global_load_dwordx4 v[78:81], v228, s[6:7] offset:608
	s_waitcnt vmcnt(45)
	v_mfma_f32_32x32x16_bf16 v[2:17], v[82:85], v[98:101], v[2:17]
	v_mfma_f32_32x32x16_bf16 v[18:33], v[82:85], v[114:117], v[18:33]
	s_waitcnt vmcnt(42)
	v_mfma_f32_32x32x16_bf16 v[2:17], v[86:89], v[102:105], v[2:17]
	v_mfma_f32_32x32x16_bf16 v[18:33], v[86:89], v[118:121], v[18:33]
	s_waitcnt vmcnt(39)
	v_mfma_f32_32x32x16_bf16 v[2:17], v[90:93], v[106:109], v[2:17]
	v_mfma_f32_32x32x16_bf16 v[18:33], v[90:93], v[122:125], v[18:33]
	s_waitcnt vmcnt(36)
	v_mfma_f32_32x32x16_bf16 v[2:17], v[94:97], v[110:113], v[2:17]
	v_mfma_f32_32x32x16_bf16 v[18:33], v[94:97], v[126:129], v[18:33]
	global_load_dwordx4 v[82:85], v226, s[20:21] offset:640
	global_load_dwordx4 v[98:101], v227, s[6:7] offset:640
	global_load_dwordx4 v[114:117], v228, s[6:7] offset:640
	global_load_dwordx4 v[86:89], v226, s[20:21] offset:672
	global_load_dwordx4 v[102:105], v227, s[6:7] offset:672
	global_load_dwordx4 v[118:121], v228, s[6:7] offset:672
	global_load_dwordx4 v[90:93], v226, s[20:21] offset:704
	global_load_dwordx4 v[106:109], v227, s[6:7] offset:704
	global_load_dwordx4 v[122:125], v228, s[6:7] offset:704
	global_load_dwordx4 v[94:97], v226, s[20:21] offset:736
	global_load_dwordx4 v[110:113], v227, s[6:7] offset:736
	global_load_dwordx4 v[126:129], v228, s[6:7] offset:736
	s_waitcnt vmcnt(45)
	v_mfma_f32_32x32x16_bf16 v[2:17], v[130:133], v[146:149], v[2:17]
	v_mfma_f32_32x32x16_bf16 v[18:33], v[130:133], v[162:165], v[18:33]
	s_waitcnt vmcnt(42)
	v_mfma_f32_32x32x16_bf16 v[2:17], v[134:137], v[150:153], v[2:17]
	v_mfma_f32_32x32x16_bf16 v[18:33], v[134:137], v[166:169], v[18:33]
	s_waitcnt vmcnt(39)
	v_mfma_f32_32x32x16_bf16 v[2:17], v[138:141], v[154:157], v[2:17]
	v_mfma_f32_32x32x16_bf16 v[18:33], v[138:141], v[170:173], v[18:33]
	s_waitcnt vmcnt(36)
	v_mfma_f32_32x32x16_bf16 v[2:17], v[142:145], v[158:161], v[2:17]
	v_mfma_f32_32x32x16_bf16 v[18:33], v[142:145], v[174:177], v[18:33]
	global_load_dwordx4 v[130:133], v226, s[20:21] offset:768
	global_load_dwordx4 v[146:149], v227, s[6:7] offset:768
	global_load_dwordx4 v[162:165], v228, s[6:7] offset:768
	global_load_dwordx4 v[134:137], v226, s[20:21] offset:800
	global_load_dwordx4 v[150:153], v227, s[6:7] offset:800
	global_load_dwordx4 v[166:169], v228, s[6:7] offset:800
	global_load_dwordx4 v[138:141], v226, s[20:21] offset:832
	global_load_dwordx4 v[154:157], v227, s[6:7] offset:832
	global_load_dwordx4 v[170:173], v228, s[6:7] offset:832
	global_load_dwordx4 v[142:145], v226, s[20:21] offset:864
	global_load_dwordx4 v[158:161], v227, s[6:7] offset:864
	global_load_dwordx4 v[174:177], v228, s[6:7] offset:864
	s_waitcnt vmcnt(45)
	v_mfma_f32_32x32x16_bf16 v[2:17], v[178:181], v[194:197], v[2:17]
	v_mfma_f32_32x32x16_bf16 v[18:33], v[178:181], v[210:213], v[18:33]
	s_waitcnt vmcnt(42)
	v_mfma_f32_32x32x16_bf16 v[2:17], v[182:185], v[198:201], v[2:17]
	v_mfma_f32_32x32x16_bf16 v[18:33], v[182:185], v[214:217], v[18:33]
	s_waitcnt vmcnt(39)
	v_mfma_f32_32x32x16_bf16 v[2:17], v[186:189], v[202:205], v[2:17]
	v_mfma_f32_32x32x16_bf16 v[18:33], v[186:189], v[218:221], v[18:33]
	s_waitcnt vmcnt(36)
	v_mfma_f32_32x32x16_bf16 v[2:17], v[190:193], v[206:209], v[2:17]
	v_mfma_f32_32x32x16_bf16 v[18:33], v[190:193], v[222:225], v[18:33]
	global_load_dwordx4 v[178:181], v226, s[20:21] offset:896
	global_load_dwordx4 v[194:197], v227, s[6:7] offset:896
	global_load_dwordx4 v[210:213], v228, s[6:7] offset:896
	global_load_dwordx4 v[182:185], v226, s[20:21] offset:928
	global_load_dwordx4 v[198:201], v227, s[6:7] offset:928
	global_load_dwordx4 v[214:217], v228, s[6:7] offset:928
	global_load_dwordx4 v[186:189], v226, s[20:21] offset:960
	global_load_dwordx4 v[202:205], v227, s[6:7] offset:960
	global_load_dwordx4 v[218:221], v228, s[6:7] offset:960
	global_load_dwordx4 v[190:193], v226, s[20:21] offset:992
	global_load_dwordx4 v[206:209], v227, s[6:7] offset:992
	global_load_dwordx4 v[222:225], v228, s[6:7] offset:992
	s_waitcnt vmcnt(45)
	v_mfma_f32_32x32x16_bf16 v[2:17], v[34:37], v[50:53], v[2:17]
	v_mfma_f32_32x32x16_bf16 v[18:33], v[34:37], v[66:69], v[18:33]
	s_waitcnt vmcnt(42)
	v_mfma_f32_32x32x16_bf16 v[2:17], v[38:41], v[54:57], v[2:17]
	v_mfma_f32_32x32x16_bf16 v[18:33], v[38:41], v[70:73], v[18:33]
	s_waitcnt vmcnt(39)
	v_mfma_f32_32x32x16_bf16 v[2:17], v[42:45], v[58:61], v[2:17]
	v_mfma_f32_32x32x16_bf16 v[18:33], v[42:45], v[74:77], v[18:33]
	s_waitcnt vmcnt(36)
	v_mfma_f32_32x32x16_bf16 v[2:17], v[46:49], v[62:65], v[2:17]
	v_mfma_f32_32x32x16_bf16 v[18:33], v[46:49], v[78:81], v[18:33]
	s_waitcnt vmcnt(33)
	v_mfma_f32_32x32x16_bf16 v[2:17], v[82:85], v[98:101], v[2:17]
	v_mfma_f32_32x32x16_bf16 v[18:33], v[82:85], v[114:117], v[18:33]
	s_waitcnt vmcnt(30)
	v_mfma_f32_32x32x16_bf16 v[2:17], v[86:89], v[102:105], v[2:17]
	v_mfma_f32_32x32x16_bf16 v[18:33], v[86:89], v[118:121], v[18:33]
	s_waitcnt vmcnt(27)
	v_mfma_f32_32x32x16_bf16 v[2:17], v[90:93], v[106:109], v[2:17]
	v_mfma_f32_32x32x16_bf16 v[18:33], v[90:93], v[122:125], v[18:33]
	s_waitcnt vmcnt(24)
	v_mfma_f32_32x32x16_bf16 v[2:17], v[94:97], v[110:113], v[2:17]
	v_mfma_f32_32x32x16_bf16 v[18:33], v[94:97], v[126:129], v[18:33]
	s_waitcnt vmcnt(21)
	v_mfma_f32_32x32x16_bf16 v[2:17], v[130:133], v[146:149], v[2:17]
	v_mfma_f32_32x32x16_bf16 v[18:33], v[130:133], v[162:165], v[18:33]
	s_waitcnt vmcnt(18)
	v_mfma_f32_32x32x16_bf16 v[2:17], v[134:137], v[150:153], v[2:17]
	v_mfma_f32_32x32x16_bf16 v[18:33], v[134:137], v[166:169], v[18:33]
	s_waitcnt vmcnt(15)
	v_mfma_f32_32x32x16_bf16 v[2:17], v[138:141], v[154:157], v[2:17]
	v_mfma_f32_32x32x16_bf16 v[18:33], v[138:141], v[170:173], v[18:33]
	s_waitcnt vmcnt(12)
	v_mfma_f32_32x32x16_bf16 v[2:17], v[142:145], v[158:161], v[2:17]
	v_mfma_f32_32x32x16_bf16 v[18:33], v[142:145], v[174:177], v[18:33]
	s_waitcnt vmcnt(9)
	v_mfma_f32_32x32x16_bf16 v[2:17], v[178:181], v[194:197], v[2:17]
	v_mfma_f32_32x32x16_bf16 v[18:33], v[178:181], v[210:213], v[18:33]
	s_waitcnt vmcnt(6)
	v_mfma_f32_32x32x16_bf16 v[2:17], v[182:185], v[198:201], v[2:17]
	v_mfma_f32_32x32x16_bf16 v[18:33], v[182:185], v[214:217], v[18:33]
	s_waitcnt vmcnt(3)
	v_mfma_f32_32x32x16_bf16 v[2:17], v[186:189], v[202:205], v[2:17]
	v_mfma_f32_32x32x16_bf16 v[18:33], v[186:189], v[218:221], v[18:33]
	s_waitcnt vmcnt(0)
	v_mfma_f32_32x32x16_bf16 v[2:17], v[190:193], v[206:209], v[2:17]
	v_mfma_f32_32x32x16_bf16 v[18:33], v[190:193], v[222:225], v[18:33]
	s_nop 15
	s_nop 3
	global_store_dword v229, v2, s[22:23]
	global_store_dword v229, v18, s[22:23] offset:128
	v_add_u32_e32 v231, 0x1000, v229
	global_store_dword v231, v3, s[22:23]
	global_store_dword v231, v19, s[22:23] offset:128
	v_add_u32_e32 v230, 0x2000, v229
	global_store_dword v230, v4, s[22:23]
	global_store_dword v230, v20, s[22:23] offset:128
	v_add_u32_e32 v231, 0x3000, v229
	global_store_dword v231, v5, s[22:23]
	global_store_dword v231, v21, s[22:23] offset:128
	v_add_u32_e32 v230, 0x8000, v229
	global_store_dword v230, v6, s[22:23]
	global_store_dword v230, v22, s[22:23] offset:128
	v_add_u32_e32 v231, 0x9000, v229
	global_store_dword v231, v7, s[22:23]
	global_store_dword v231, v23, s[22:23] offset:128
	v_add_u32_e32 v230, 0xa000, v229
	global_store_dword v230, v8, s[22:23]
	global_store_dword v230, v24, s[22:23] offset:128
	v_add_u32_e32 v231, 0xb000, v229
	global_store_dword v231, v9, s[22:23]
	global_store_dword v231, v25, s[22:23] offset:128
	v_add_u32_e32 v230, 0x10000, v229
	global_store_dword v230, v10, s[22:23]
	global_store_dword v230, v26, s[22:23] offset:128
	v_add_u32_e32 v231, 0x11000, v229
	global_store_dword v231, v11, s[22:23]
	global_store_dword v231, v27, s[22:23] offset:128
	v_add_u32_e32 v230, 0x12000, v229
	global_store_dword v230, v12, s[22:23]
	global_store_dword v230, v28, s[22:23] offset:128
	v_add_u32_e32 v231, 0x13000, v229
	global_store_dword v231, v13, s[22:23]
	global_store_dword v231, v29, s[22:23] offset:128
	v_add_u32_e32 v230, 0x18000, v229
	global_store_dword v230, v14, s[22:23]
	global_store_dword v230, v30, s[22:23] offset:128
	v_add_u32_e32 v231, 0x19000, v229
	global_store_dword v231, v15, s[22:23]
	global_store_dword v231, v31, s[22:23] offset:128
	v_add_u32_e32 v230, 0x1a000, v229
	global_store_dword v230, v16, s[22:23]
	global_store_dword v230, v32, s[22:23] offset:128
	v_add_u32_e32 v231, 0x1b000, v229
	global_store_dword v231, v17, s[22:23]
	global_store_dword v231, v33, s[22:23] offset:128
	s_add_i32 s12, s12, s24
	s_cmpk_lt_i32 s12, 0x200
	s_cbranch_scc1 .Lsg3_unit

.Lsg6_unit:
	s_and_b32 s28, s14, 7
	s_lshr_b32 s29, s14, 3
	s_and_b32 s25, s29, 7
	s_lshr_b32 s29, s29, 3
	s_lshr_b32 s26, s29, 1
	s_and_b32 s27, s29, 1
	s_lshl_b32 s27, s27, 3
	s_add_u32 s27, s27, s28
	s_lshl_b32 s30, s25, 10
	s_lshl_b32 s31, s27, 18
	s_add_u32 s31, s31, s30
	s_lshl_b32 s33, s26, 19
	s_add_u32 s33, s33, s30
	v_add_u32_e32 v226, s31, v232
	v_add_u32_e32 v227, s33, v232
	v_add_u32_e32 v228, 0x40000, v227
	s_lshl_b32 s34, s25, 21
	s_lshl_b32 s35, s27, 17
	s_add_u32 s34, s34, s35
	s_lshl_b32 s35, s26, 8
	s_add_u32 s34, s34, s35
	v_add_u32_e32 v229, s34, v233
	global_load_dwordx4 v[34:37], v226, s[20:21] offset:0
	global_load_dwordx4 v[50:53], v227, s[6:7] offset:0
	global_load_dwordx4 v[66:69], v228, s[6:7] offset:0
	global_load_dwordx4 v[38:41], v226, s[20:21] offset:32
	global_load_dwordx4 v[54:57], v227, s[6:7] offset:32
	global_load_dwordx4 v[70:73], v228, s[6:7] offset:32
	global_load_dwordx4 v[42:45], v226, s[20:21] offset:64
	global_load_dwordx4 v[58:61], v227, s[6:7] offset:64
	global_load_dwordx4 v[74:77], v228, s[6:7] offset:64
	global_load_dwordx4 v[46:49], v226, s[20:21] offset:96
	global_load_dwordx4 v[62:65], v227, s[6:7] offset:96
	global_load_dwordx4 v[78:81], v228, s[6:7] offset:96
	global_load_dwordx4 v[82:85], v226, s[20:21] offset:128
	global_load_dwordx4 v[98:101], v227, s[6:7] offset:128
	global_load_dwordx4 v[114:117], v228, s[6:7] offset:128
	global_load_dwordx4 v[86:89], v226, s[20:21] offset:160
	global_load_dwordx4 v[102:105], v227, s[6:7] offset:160
	global_load_dwordx4 v[118:121], v228, s[6:7] offset:160
	global_load_dwordx4 v[90:93], v226, s[20:21] offset:192
	global_load_dwordx4 v[106:109], v227, s[6:7] offset:192
	global_load_dwordx4 v[122:125], v228, s[6:7] offset:192
	global_load_dwordx4 v[94:97], v226, s[20:21] offset:224
	global_load_dwordx4 v[110:113], v227, s[6:7] offset:224
	global_load_dwordx4 v[126:129], v228, s[6:7] offset:224
	global_load_dwordx4 v[130:133], v226, s[20:21] offset:256
	global_load_dwordx4 v[146:149], v227, s[6:7] offset:256
	global_load_dwordx4 v[162:165], v228, s[6:7] offset:256
	global_load_dwordx4 v[134:137], v226, s[20:21] offset:288
	global_load_dwordx4 v[150:153], v227, s[6:7] offset:288
	global_load_dwordx4 v[166:169], v228, s[6:7] offset:288
	global_load_dwordx4 v[138:141], v226, s[20:21] offset:320
	global_load_dwordx4 v[154:157], v227, s[6:7] offset:320
	global_load_dwordx4 v[170:173], v228, s[6:7] offset:320
	global_load_dwordx4 v[142:145], v226, s[20:21] offset:352
	global_load_dwordx4 v[158:161], v227, s[6:7] offset:352
	global_load_dwordx4 v[174:177], v228, s[6:7] offset:352
	global_load_dwordx4 v[178:181], v226, s[20:21] offset:384
	global_load_dwordx4 v[194:197], v227, s[6:7] offset:384
	global_load_dwordx4 v[210:213], v228, s[6:7] offset:384
	global_load_dwordx4 v[182:185], v226, s[20:21] offset:416
	global_load_dwordx4 v[198:201], v227, s[6:7] offset:416
	global_load_dwordx4 v[214:217], v228, s[6:7] offset:416
	global_load_dwordx4 v[186:189], v226, s[20:21] offset:448
	global_load_dwordx4 v[202:205], v227, s[6:7] offset:448
	global_load_dwordx4 v[218:221], v228, s[6:7] offset:448
	global_load_dwordx4 v[190:193], v226, s[20:21] offset:480
	global_load_dwordx4 v[206:209], v227, s[6:7] offset:480
	global_load_dwordx4 v[222:225], v228, s[6:7] offset:480
	s_waitcnt vmcnt(45)
	v_mfma_f32_32x32x16_bf16 v[2:17], v[34:37], v[50:53], 0
	v_mfma_f32_32x32x16_bf16 v[18:33], v[34:37], v[66:69], 0
	s_waitcnt vmcnt(42)
	v_mfma_f32_32x32x16_bf16 v[2:17], v[38:41], v[54:57], v[2:17]
	v_mfma_f32_32x32x16_bf16 v[18:33], v[38:41], v[70:73], v[18:33]
	s_waitcnt vmcnt(39)
	v_mfma_f32_32x32x16_bf16 v[2:17], v[42:45], v[58:61], v[2:17]
	v_mfma_f32_32x32x16_bf16 v[18:33], v[42:45], v[74:77], v[18:33]
	s_waitcnt vmcnt(36)
	v_mfma_f32_32x32x16_bf16 v[2:17], v[46:49], v[62:65], v[2:17]
	v_mfma_f32_32x32x16_bf16 v[18:33], v[46:49], v[78:81], v[18:33]
	global_load_dwordx4 v[34:37], v226, s[20:21] offset:512
	global_load_dwordx4 v[50:53], v227, s[6:7] offset:512
	global_load_dwordx4 v[66:69], v228, s[6:7] offset:512
	global_load_dwordx4 v[38:41], v226, s[20:21] offset:544
	global_load_dwordx4 v[54:57], v227, s[6:7] offset:544
	global_load_dwordx4 v[70:73], v228, s[6:7] offset:544
	global_load_dwordx4 v[42:45], v226, s[20:21] offset:576
	global_load_dwordx4 v[58:61], v227, s[6:7] offset:576
	global_load_dwordx4 v[74:77], v228, s[6:7] offset:576
	global_load_dwordx4 v[46:49], v226, s[20:21] offset:608
	global_load_dwordx4 v[62:65], v227, s[6:7] offset:608
	global_load_dwordx4 v[78:81], v228, s[6:7] offset:608
	s_waitcnt vmcnt(45)
	v_mfma_f32_32x32x16_bf16 v[2:17], v[82:85], v[98:101], v[2:17]
	v_mfma_f32_32x32x16_bf16 v[18:33], v[82:85], v[114:117], v[18:33]
	s_waitcnt vmcnt(42)
	v_mfma_f32_32x32x16_bf16 v[2:17], v[86:89], v[102:105], v[2:17]
	v_mfma_f32_32x32x16_bf16 v[18:33], v[86:89], v[118:121], v[18:33]
	s_waitcnt vmcnt(39)
	v_mfma_f32_32x32x16_bf16 v[2:17], v[90:93], v[106:109], v[2:17]
	v_mfma_f32_32x32x16_bf16 v[18:33], v[90:93], v[122:125], v[18:33]
	s_waitcnt vmcnt(36)
	v_mfma_f32_32x32x16_bf16 v[2:17], v[94:97], v[110:113], v[2:17]
	v_mfma_f32_32x32x16_bf16 v[18:33], v[94:97], v[126:129], v[18:33]
	global_load_dwordx4 v[82:85], v226, s[20:21] offset:640
	global_load_dwordx4 v[98:101], v227, s[6:7] offset:640
	global_load_dwordx4 v[114:117], v228, s[6:7] offset:640
	global_load_dwordx4 v[86:89], v226, s[20:21] offset:672
	global_load_dwordx4 v[102:105], v227, s[6:7] offset:672
	global_load_dwordx4 v[118:121], v228, s[6:7] offset:672
	global_load_dwordx4 v[90:93], v226, s[20:21] offset:704
	global_load_dwordx4 v[106:109], v227, s[6:7] offset:704
	global_load_dwordx4 v[122:125], v228, s[6:7] offset:704
	global_load_dwordx4 v[94:97], v226, s[20:21] offset:736
	global_load_dwordx4 v[110:113], v227, s[6:7] offset:736
	global_load_dwordx4 v[126:129], v228, s[6:7] offset:736
	s_waitcnt vmcnt(45)
	v_mfma_f32_32x32x16_bf16 v[2:17], v[130:133], v[146:149], v[2:17]
	v_mfma_f32_32x32x16_bf16 v[18:33], v[130:133], v[162:165], v[18:33]
	s_waitcnt vmcnt(42)
	v_mfma_f32_32x32x16_bf16 v[2:17], v[134:137], v[150:153], v[2:17]
	v_mfma_f32_32x32x16_bf16 v[18:33], v[134:137], v[166:169], v[18:33]
	s_waitcnt vmcnt(39)
	v_mfma_f32_32x32x16_bf16 v[2:17], v[138:141], v[154:157], v[2:17]
	v_mfma_f32_32x32x16_bf16 v[18:33], v[138:141], v[170:173], v[18:33]
	s_waitcnt vmcnt(36)
	v_mfma_f32_32x32x16_bf16 v[2:17], v[142:145], v[158:161], v[2:17]
	v_mfma_f32_32x32x16_bf16 v[18:33], v[142:145], v[174:177], v[18:33]
	global_load_dwordx4 v[130:133], v226, s[20:21] offset:768
	global_load_dwordx4 v[146:149], v227, s[6:7] offset:768
	global_load_dwordx4 v[162:165], v228, s[6:7] offset:768
	global_load_dwordx4 v[134:137], v226, s[20:21] offset:800
	global_load_dwordx4 v[150:153], v227, s[6:7] offset:800
	global_load_dwordx4 v[166:169], v228, s[6:7] offset:800
	global_load_dwordx4 v[138:141], v226, s[20:21] offset:832
	global_load_dwordx4 v[154:157], v227, s[6:7] offset:832
	global_load_dwordx4 v[170:173], v228, s[6:7] offset:832
	global_load_dwordx4 v[142:145], v226, s[20:21] offset:864
	global_load_dwordx4 v[158:161], v227, s[6:7] offset:864
	global_load_dwordx4 v[174:177], v228, s[6:7] offset:864
	s_waitcnt vmcnt(45)
	v_mfma_f32_32x32x16_bf16 v[2:17], v[178:181], v[194:197], v[2:17]
	v_mfma_f32_32x32x16_bf16 v[18:33], v[178:181], v[210:213], v[18:33]
	s_waitcnt vmcnt(42)
	v_mfma_f32_32x32x16_bf16 v[2:17], v[182:185], v[198:201], v[2:17]
	v_mfma_f32_32x32x16_bf16 v[18:33], v[182:185], v[214:217], v[18:33]
	s_waitcnt vmcnt(39)
	v_mfma_f32_32x32x16_bf16 v[2:17], v[186:189], v[202:205], v[2:17]
	v_mfma_f32_32x32x16_bf16 v[18:33], v[186:189], v[218:221], v[18:33]
	s_waitcnt vmcnt(36)
	v_mfma_f32_32x32x16_bf16 v[2:17], v[190:193], v[206:209], v[2:17]
	v_mfma_f32_32x32x16_bf16 v[18:33], v[190:193], v[222:225], v[18:33]
	global_load_dwordx4 v[178:181], v226, s[20:21] offset:896
	global_load_dwordx4 v[194:197], v227, s[6:7] offset:896
	global_load_dwordx4 v[210:213], v228, s[6:7] offset:896
	global_load_dwordx4 v[182:185], v226, s[20:21] offset:928
	global_load_dwordx4 v[198:201], v227, s[6:7] offset:928
	global_load_dwordx4 v[214:217], v228, s[6:7] offset:928
	global_load_dwordx4 v[186:189], v226, s[20:21] offset:960
	global_load_dwordx4 v[202:205], v227, s[6:7] offset:960
	global_load_dwordx4 v[218:221], v228, s[6:7] offset:960
	global_load_dwordx4 v[190:193], v226, s[20:21] offset:992
	global_load_dwordx4 v[206:209], v227, s[6:7] offset:992
	global_load_dwordx4 v[222:225], v228, s[6:7] offset:992
	s_waitcnt vmcnt(45)
	v_mfma_f32_32x32x16_bf16 v[2:17], v[34:37], v[50:53], v[2:17]
	v_mfma_f32_32x32x16_bf16 v[18:33], v[34:37], v[66:69], v[18:33]
	s_waitcnt vmcnt(42)
	v_mfma_f32_32x32x16_bf16 v[2:17], v[38:41], v[54:57], v[2:17]
	v_mfma_f32_32x32x16_bf16 v[18:33], v[38:41], v[70:73], v[18:33]
	s_waitcnt vmcnt(39)
	v_mfma_f32_32x32x16_bf16 v[2:17], v[42:45], v[58:61], v[2:17]
	v_mfma_f32_32x32x16_bf16 v[18:33], v[42:45], v[74:77], v[18:33]
	s_waitcnt vmcnt(36)
	v_mfma_f32_32x32x16_bf16 v[2:17], v[46:49], v[62:65], v[2:17]
	v_mfma_f32_32x32x16_bf16 v[18:33], v[46:49], v[78:81], v[18:33]
	s_waitcnt vmcnt(33)
	v_mfma_f32_32x32x16_bf16 v[2:17], v[82:85], v[98:101], v[2:17]
	v_mfma_f32_32x32x16_bf16 v[18:33], v[82:85], v[114:117], v[18:33]
	s_waitcnt vmcnt(30)
	v_mfma_f32_32x32x16_bf16 v[2:17], v[86:89], v[102:105], v[2:17]
	v_mfma_f32_32x32x16_bf16 v[18:33], v[86:89], v[118:121], v[18:33]
	s_waitcnt vmcnt(27)
	v_mfma_f32_32x32x16_bf16 v[2:17], v[90:93], v[106:109], v[2:17]
	v_mfma_f32_32x32x16_bf16 v[18:33], v[90:93], v[122:125], v[18:33]
	s_waitcnt vmcnt(24)
	v_mfma_f32_32x32x16_bf16 v[2:17], v[94:97], v[110:113], v[2:17]
	v_mfma_f32_32x32x16_bf16 v[18:33], v[94:97], v[126:129], v[18:33]
	s_waitcnt vmcnt(21)
	v_mfma_f32_32x32x16_bf16 v[2:17], v[130:133], v[146:149], v[2:17]
	v_mfma_f32_32x32x16_bf16 v[18:33], v[130:133], v[162:165], v[18:33]
	s_waitcnt vmcnt(18)
	v_mfma_f32_32x32x16_bf16 v[2:17], v[134:137], v[150:153], v[2:17]
	v_mfma_f32_32x32x16_bf16 v[18:33], v[134:137], v[166:169], v[18:33]
	s_waitcnt vmcnt(15)
	v_mfma_f32_32x32x16_bf16 v[2:17], v[138:141], v[154:157], v[2:17]
	v_mfma_f32_32x32x16_bf16 v[18:33], v[138:141], v[170:173], v[18:33]
	s_waitcnt vmcnt(12)
	v_mfma_f32_32x32x16_bf16 v[2:17], v[142:145], v[158:161], v[2:17]
	v_mfma_f32_32x32x16_bf16 v[18:33], v[142:145], v[174:177], v[18:33]
	s_waitcnt vmcnt(9)
	v_mfma_f32_32x32x16_bf16 v[2:17], v[178:181], v[194:197], v[2:17]
	v_mfma_f32_32x32x16_bf16 v[18:33], v[178:181], v[210:213], v[18:33]
	s_waitcnt vmcnt(6)
	v_mfma_f32_32x32x16_bf16 v[2:17], v[182:185], v[198:201], v[2:17]
	v_mfma_f32_32x32x16_bf16 v[18:33], v[182:185], v[214:217], v[18:33]
	s_waitcnt vmcnt(3)
	v_mfma_f32_32x32x16_bf16 v[2:17], v[186:189], v[202:205], v[2:17]
	v_mfma_f32_32x32x16_bf16 v[18:33], v[186:189], v[218:221], v[18:33]
	s_waitcnt vmcnt(0)
	v_mfma_f32_32x32x16_bf16 v[2:17], v[190:193], v[206:209], v[2:17]
	v_mfma_f32_32x32x16_bf16 v[18:33], v[190:193], v[222:225], v[18:33]
	s_nop 15
	s_nop 3
	global_store_dword v229, v2, s[22:23]
	global_store_dword v229, v18, s[22:23] offset:128
	v_add_u32_e32 v231, 0x1000, v229
	global_store_dword v231, v3, s[22:23]
	global_store_dword v231, v19, s[22:23] offset:128
	v_add_u32_e32 v230, 0x2000, v229
	global_store_dword v230, v4, s[22:23]
	global_store_dword v230, v20, s[22:23] offset:128
	v_add_u32_e32 v231, 0x3000, v229
	global_store_dword v231, v5, s[22:23]
	global_store_dword v231, v21, s[22:23] offset:128
	v_add_u32_e32 v230, 0x8000, v229
	global_store_dword v230, v6, s[22:23]
	global_store_dword v230, v22, s[22:23] offset:128
	v_add_u32_e32 v231, 0x9000, v229
	global_store_dword v231, v7, s[22:23]
	global_store_dword v231, v23, s[22:23] offset:128
	v_add_u32_e32 v230, 0xa000, v229
	global_store_dword v230, v8, s[22:23]
	global_store_dword v230, v24, s[22:23] offset:128
	v_add_u32_e32 v231, 0xb000, v229
	global_store_dword v231, v9, s[22:23]
	global_store_dword v231, v25, s[22:23] offset:128
	v_add_u32_e32 v230, 0x10000, v229
	global_store_dword v230, v10, s[22:23]
	global_store_dword v230, v26, s[22:23] offset:128
	v_add_u32_e32 v231, 0x11000, v229
	global_store_dword v231, v11, s[22:23]
	global_store_dword v231, v27, s[22:23] offset:128
	v_add_u32_e32 v230, 0x12000, v229
	global_store_dword v230, v12, s[22:23]
	global_store_dword v230, v28, s[22:23] offset:128
	v_add_u32_e32 v231, 0x13000, v229
	global_store_dword v231, v13, s[22:23]
	global_store_dword v231, v29, s[22:23] offset:128
	v_add_u32_e32 v230, 0x18000, v229
	global_store_dword v230, v14, s[22:23]
	global_store_dword v230, v30, s[22:23] offset:128
	v_add_u32_e32 v231, 0x19000, v229
	global_store_dword v231, v15, s[22:23]
	global_store_dword v231, v31, s[22:23] offset:128
	v_add_u32_e32 v230, 0x1a000, v229
	global_store_dword v230, v16, s[22:23]
	global_store_dword v230, v32, s[22:23] offset:128
	v_add_u32_e32 v231, 0x1b000, v229
	global_store_dword v231, v17, s[22:23]
	global_store_dword v231, v33, s[22:23] offset:128
	s_add_i32 s14, s14, s24
	s_cmpk_lt_i32 s14, 0x800
	s_cbranch_scc1 .Lsg6_unit

.LBB9_84:
	s_andn2_b64 vcc, exec, s[4:5]
	s_cbranch_vccnz .LBB9_172
	s_and_b32 s3, s2, 0xffffffc0
	s_add_i32 s4, s2, 0x380
	s_cmp_eq_u32 s3, 64
	s_cselect_b32 s15, s4, -1
	s_add_i32 s3, s2, 0x2c0
	s_cmp_gt_i32 s2, 63
	s_cselect_b32 s33, s3, -1
	s_add_i32 s48, s2, 0xffffff00
	s_add_i32 s3, s2, 0x400
	s_cmp_lt_i32 s2, 64
	v_mbcnt_lo_u32_b32 v2, -1, 0
	s_cselect_b32 s49, s3, -1
	s_mov_b32 s13, 0
	s_movk_i32 s50, 0x1800
	s_movk_i32 s51, 0x500
	s_movk_i32 s52, 0x1ff
	s_add_i32 s53, 0, 0x12c00
	s_movk_i32 s54, 0x27f
	s_mov_b32 s14, 0x3fb8aa3b
	s_movk_i32 s55, 0xc00
	s_add_i32 s56, 0, 0x13400
	s_movk_i32 s57, 0x2ff
	v_mov_b32_e32 v69, 0
	s_mov_b64 s[16:17], 0x20000
	s_movk_i32 s58, 0x110
	s_mov_b32 s59, 0x41000000
	s_mov_b64 s[18:19], 0xd700000
	s_mov_b32 s60, 0xd700000
	v_mov_b32_e32 v1, 0xfffffd80
	v_mov_b32_e32 v131, 0xc1
	v_mov_b32_e32 v133, 0x2c2
	v_mbcnt_hi_u32_b32 v139, -1, v2
	s_mov_b32 s74, 0
	s_mov_b32 s61, 0
	s_branch .LBB9_88

.LBB9_101:
	s_add_i32 s75, s6, 1
	s_cmp_eq_u32 s74, s75
	s_cbranch_scc0 .Ltbl9_load
	s_mov_b64 s[38:39], exec
	s_branch .LBB9_114
.Ltbl9_load:
	s_mov_b32 s74, s75
	v_cmp_gt_i32_e32 vcc, s51, v34
	s_and_saveexec_b64 s[38:39], vcc
	s_cbranch_execz .LBB9_114
	s_mul_i32 s12, s6, 0x402
	v_max_i32_e32 v2, 0x300, v34
	s_lshl_b64 s[4:5], s[12:13], 2
	v_sub_u32_e32 v2, v2, v34
	s_waitcnt lgkmcnt(0)
	s_add_u32 s40, s2, s4
	v_add_u32_e32 v3, 0x1ff, v2
	s_addc_u32 s41, s3, s5
	v_cmp_lt_u32_e32 vcc, s52, v3
	s_mov_b64 s[2:3], -1
	v_mov_b32_e32 v2, v34
	s_and_saveexec_b64 s[42:43], vcc
	s_cbranch_execz .LBB9_111
	v_lshrrev_b32_e32 v4, 9, v3
	v_add_u32_e32 v2, -1, v4
	v_add_u32_e32 v35, 0x200, v34
	v_lshrrev_b32_e32 v3, 1, v2
	v_add_u32_e32 v5, 1, v3
	v_cmp_lt_u32_e32 vcc, 5, v2
	v_mov_b32_e32 v8, 0
	v_mov_b64_e32 v[2:3], v[34:35]
	s_and_saveexec_b64 s[44:45], vcc
	s_cbranch_execz .LBB9_107
	v_and_b32_e32 v6, -4, v5
	v_lshl_add_u32 v7, v34, 2, s53
	s_mov_b32 s12, 0
	s_mov_b64 s[46:47], 0
	v_mov_b64_e32 v[2:3], v[34:35]

	.amdhsa_kernel _Z10fwd_kernelILi9ELi10EEv4Args
		.amdhsa_group_segment_fixed_size 0
		.amdhsa_private_segment_fixed_size 0
		.amdhsa_kernarg_size 488
		.amdhsa_user_sgpr_count 2
		.amdhsa_user_sgpr_dispatch_ptr 0
		.amdhsa_user_sgpr_queue_ptr 0
		.amdhsa_user_sgpr_kernarg_segment_ptr 1
		.amdhsa_user_sgpr_dispatch_id 0
		.amdhsa_user_sgpr_kernarg_preload_length 0
		.amdhsa_user_sgpr_kernarg_preload_offset 0
		.amdhsa_user_sgpr_private_segment_size 0
		.amdhsa_uses_dynamic_stack 0
		.amdhsa_enable_private_segment 0
		.amdhsa_system_sgpr_workgroup_id_x 1
		.amdhsa_system_sgpr_workgroup_id_y 0
		.amdhsa_system_sgpr_workgroup_id_z 0
		.amdhsa_system_sgpr_workgroup_info 0
		.amdhsa_system_vgpr_workitem_id 0
		.amdhsa_next_free_vgpr 174
		.amdhsa_next_free_sgpr 76
		.amdhsa_accum_offset 176
		.amdhsa_reserve_vcc 1
		.amdhsa_float_round_mode_32 0
		.amdhsa_float_round_mode_16_64 0
		.amdhsa_float_denorm_mode_32 3
		.amdhsa_float_denorm_mode_16_64 3
		.amdhsa_dx10_clamp 1
		.amdhsa_ieee_mode 1
		.amdhsa_fp16_overflow 0
		.amdhsa_tg_split 0
		.amdhsa_exception_fp_ieee_invalid_op 0
		.amdhsa_exception_fp_denorm_src 0
		.amdhsa_exception_fp_ieee_div_zero 0
		.amdhsa_exception_fp_ieee_overflow 0
		.amdhsa_exception_fp_ieee_underflow 0
		.amdhsa_exception_fp_ieee_inexact 0
		.amdhsa_exception_int_div_zero 0
	.end_amdhsa_kernel

.Lsg10_unit:
	s_and_b32 s28, s12, 0xff
	s_lshr_b32 s29, s12, 8
	s_and_b32 s26, s28, 7
	s_lshl_b32 s26, s26, 1
	s_lshr_b32 s28, s28, 3
	s_lshr_b32 s25, s28, 4
	s_add_u32 s26, s26, s25
	s_bfe_u32 s25, s28, 0x10003
	s_and_b32 s27, s28, 7
	s_lshl_b32 s29, s29, 3
	s_add_u32 s27, s27, s29
	s_lshl_b32 s30, s25, 10
	s_lshl_b32 s31, s27, 16
	s_add_u32 s31, s31, s30
	s_lshl_b32 s33, s26, 17
	s_add_u32 s33, s33, s30
	v_add_u32_e32 v226, s31, v232
	v_add_u32_e32 v227, s33, v232
	v_add_u32_e32 v228, 0x10000, v227
	s_lshl_b32 s34, s25, 21
	s_lshl_b32 s35, s27, 17
	s_add_u32 s34, s34, s35
	s_lshl_b32 s35, s26, 8
	s_add_u32 s34, s34, s35
	v_add_u32_e32 v229, s34, v233
	global_load_dwordx4 v[34:37], v226, s[20:21] offset:0
	global_load_dwordx4 v[50:53], v227, s[4:5] offset:0
	global_load_dwordx4 v[66:69], v228, s[4:5] offset:0
	global_load_dwordx4 v[38:41], v226, s[20:21] offset:32
	global_load_dwordx4 v[54:57], v227, s[4:5] offset:32
	global_load_dwordx4 v[70:73], v228, s[4:5] offset:32
	global_load_dwordx4 v[42:45], v226, s[20:21] offset:64
	global_load_dwordx4 v[58:61], v227, s[4:5] offset:64
	global_load_dwordx4 v[74:77], v228, s[4:5] offset:64
	global_load_dwordx4 v[46:49], v226, s[20:21] offset:96
	global_load_dwordx4 v[62:65], v227, s[4:5] offset:96
	global_load_dwordx4 v[78:81], v228, s[4:5] offset:96
	global_load_dwordx4 v[82:85], v226, s[20:21] offset:128
	global_load_dwordx4 v[98:101], v227, s[4:5] offset:128
	global_load_dwordx4 v[114:117], v228, s[4:5] offset:128
	global_load_dwordx4 v[86:89], v226, s[20:21] offset:160
	global_load_dwordx4 v[102:105], v227, s[4:5] offset:160
	global_load_dwordx4 v[118:121], v228, s[4:5] offset:160
	global_load_dwordx4 v[90:93], v226, s[20:21] offset:192
	global_load_dwordx4 v[106:109], v227, s[4:5] offset:192
	global_load_dwordx4 v[122:125], v228, s[4:5] offset:192
	global_load_dwordx4 v[94:97], v226, s[20:21] offset:224
	global_load_dwordx4 v[110:113], v227, s[4:5] offset:224
	global_load_dwordx4 v[126:129], v228, s[4:5] offset:224
	global_load_dwordx4 v[130:133], v226, s[20:21] offset:256
	global_load_dwordx4 v[146:149], v227, s[4:5] offset:256
	global_load_dwordx4 v[162:165], v228, s[4:5] offset:256
	global_load_dwordx4 v[134:137], v226, s[20:21] offset:288
	global_load_dwordx4 v[150:153], v227, s[4:5] offset:288
	global_load_dwordx4 v[166:169], v228, s[4:5] offset:288
	global_load_dwordx4 v[138:141], v226, s[20:21] offset:320
	global_load_dwordx4 v[154:157], v227, s[4:5] offset:320
	global_load_dwordx4 v[170:173], v228, s[4:5] offset:320
	global_load_dwordx4 v[142:145], v226, s[20:21] offset:352
	global_load_dwordx4 v[158:161], v227, s[4:5] offset:352
	global_load_dwordx4 v[174:177], v228, s[4:5] offset:352
	global_load_dwordx4 v[178:181], v226, s[20:21] offset:384
	global_load_dwordx4 v[194:197], v227, s[4:5] offset:384
	global_load_dwordx4 v[210:213], v228, s[4:5] offset:384
	global_load_dwordx4 v[182:185], v226, s[20:21] offset:416
	global_load_dwordx4 v[198:201], v227, s[4:5] offset:416
	global_load_dwordx4 v[214:217], v228, s[4:5] offset:416
	global_load_dwordx4 v[186:189], v226, s[20:21] offset:448
	global_load_dwordx4 v[202:205], v227, s[4:5] offset:448
	global_load_dwordx4 v[218:221], v228, s[4:5] offset:448
	global_load_dwordx4 v[190:193], v226, s[20:21] offset:480
	global_load_dwordx4 v[206:209], v227, s[4:5] offset:480
	global_load_dwordx4 v[222:225], v228, s[4:5] offset:480
	s_waitcnt vmcnt(45)
	v_mfma_f32_32x32x16_bf16 v[2:17], v[34:37], v[50:53], 0
	v_mfma_f32_32x32x16_bf16 v[18:33], v[34:37], v[66:69], 0
	s_waitcnt vmcnt(42)
	v_mfma_f32_32x32x16_bf16 v[2:17], v[38:41], v[54:57], v[2:17]
	v_mfma_f32_32x32x16_bf16 v[18:33], v[38:41], v[70:73], v[18:33]
	s_waitcnt vmcnt(39)
	v_mfma_f32_32x32x16_bf16 v[2:17], v[42:45], v[58:61], v[2:17]
	v_mfma_f32_32x32x16_bf16 v[18:33], v[42:45], v[74:77], v[18:33]
	s_waitcnt vmcnt(36)
	v_mfma_f32_32x32x16_bf16 v[2:17], v[46:49], v[62:65], v[2:17]
	v_mfma_f32_32x32x16_bf16 v[18:33], v[46:49], v[78:81], v[18:33]
	global_load_dwordx4 v[34:37], v226, s[20:21] offset:512
	global_load_dwordx4 v[50:53], v227, s[4:5] offset:512
	global_load_dwordx4 v[66:69], v228, s[4:5] offset:512
	global_load_dwordx4 v[38:41], v226, s[20:21] offset:544
	global_load_dwordx4 v[54:57], v227, s[4:5] offset:544
	global_load_dwordx4 v[70:73], v228, s[4:5] offset:544
	global_load_dwordx4 v[42:45], v226, s[20:21] offset:576
	global_load_dwordx4 v[58:61], v227, s[4:5] offset:576
	global_load_dwordx4 v[74:77], v228, s[4:5] offset:576
	global_load_dwordx4 v[46:49], v226, s[20:21] offset:608
	global_load_dwordx4 v[62:65], v227, s[4:5] offset:608
	global_load_dwordx4 v[78:81], v228, s[4:5] offset:608
	s_waitcnt vmcnt(45)
	v_mfma_f32_32x32x16_bf16 v[2:17], v[82:85], v[98:101], v[2:17]
	v_mfma_f32_32x32x16_bf16 v[18:33], v[82:85], v[114:117], v[18:33]
	s_waitcnt vmcnt(42)
	v_mfma_f32_32x32x16_bf16 v[2:17], v[86:89], v[102:105], v[2:17]
	v_mfma_f32_32x32x16_bf16 v[18:33], v[86:89], v[118:121], v[18:33]
	s_waitcnt vmcnt(39)
	v_mfma_f32_32x32x16_bf16 v[2:17], v[90:93], v[106:109], v[2:17]
	v_mfma_f32_32x32x16_bf16 v[18:33], v[90:93], v[122:125], v[18:33]
	s_waitcnt vmcnt(36)
	v_mfma_f32_32x32x16_bf16 v[2:17], v[94:97], v[110:113], v[2:17]
	v_mfma_f32_32x32x16_bf16 v[18:33], v[94:97], v[126:129], v[18:33]
	global_load_dwordx4 v[82:85], v226, s[20:21] offset:640
	global_load_dwordx4 v[98:101], v227, s[4:5] offset:640
	global_load_dwordx4 v[114:117], v228, s[4:5] offset:640
	global_load_dwordx4 v[86:89], v226, s[20:21] offset:672
	global_load_dwordx4 v[102:105], v227, s[4:5] offset:672
	global_load_dwordx4 v[118:121], v228, s[4:5] offset:672
	global_load_dwordx4 v[90:93], v226, s[20:21] offset:704
	global_load_dwordx4 v[106:109], v227, s[4:5] offset:704
	global_load_dwordx4 v[122:125], v228, s[4:5] offset:704
	global_load_dwordx4 v[94:97], v226, s[20:21] offset:736
	global_load_dwordx4 v[110:113], v227, s[4:5] offset:736
	global_load_dwordx4 v[126:129], v228, s[4:5] offset:736
	s_waitcnt vmcnt(45)
	v_mfma_f32_32x32x16_bf16 v[2:17], v[130:133], v[146:149], v[2:17]
	v_mfma_f32_32x32x16_bf16 v[18:33], v[130:133], v[162:165], v[18:33]
	s_waitcnt vmcnt(42)
	v_mfma_f32_32x32x16_bf16 v[2:17], v[134:137], v[150:153], v[2:17]
	v_mfma_f32_32x32x16_bf16 v[18:33], v[134:137], v[166:169], v[18:33]
	s_waitcnt vmcnt(39)
	v_mfma_f32_32x32x16_bf16 v[2:17], v[138:141], v[154:157], v[2:17]
	v_mfma_f32_32x32x16_bf16 v[18:33], v[138:141], v[170:173], v[18:33]
	s_waitcnt vmcnt(36)
	v_mfma_f32_32x32x16_bf16 v[2:17], v[142:145], v[158:161], v[2:17]
	v_mfma_f32_32x32x16_bf16 v[18:33], v[142:145], v[174:177], v[18:33]
	global_load_dwordx4 v[130:133], v226, s[20:21] offset:768
	global_load_dwordx4 v[146:149], v227, s[4:5] offset:768
	global_load_dwordx4 v[162:165], v228, s[4:5] offset:768
	global_load_dwordx4 v[134:137], v226, s[20:21] offset:800
	global_load_dwordx4 v[150:153], v227, s[4:5] offset:800
	global_load_dwordx4 v[166:169], v228, s[4:5] offset:800
	global_load_dwordx4 v[138:141], v226, s[20:21] offset:832
	global_load_dwordx4 v[154:157], v227, s[4:5] offset:832
	global_load_dwordx4 v[170:173], v228, s[4:5] offset:832
	global_load_dwordx4 v[142:145], v226, s[20:21] offset:864
	global_load_dwordx4 v[158:161], v227, s[4:5] offset:864
	global_load_dwordx4 v[174:177], v228, s[4:5] offset:864
	s_waitcnt vmcnt(45)
	v_mfma_f32_32x32x16_bf16 v[2:17], v[178:181], v[194:197], v[2:17]
	v_mfma_f32_32x32x16_bf16 v[18:33], v[178:181], v[210:213], v[18:33]
	s_waitcnt vmcnt(42)
	v_mfma_f32_32x32x16_bf16 v[2:17], v[182:185], v[198:201], v[2:17]
	v_mfma_f32_32x32x16_bf16 v[18:33], v[182:185], v[214:217], v[18:33]
	s_waitcnt vmcnt(39)
	v_mfma_f32_32x32x16_bf16 v[2:17], v[186:189], v[202:205], v[2:17]
	v_mfma_f32_32x32x16_bf16 v[18:33], v[186:189], v[218:221], v[18:33]
	s_waitcnt vmcnt(36)
	v_mfma_f32_32x32x16_bf16 v[2:17], v[190:193], v[206:209], v[2:17]
	v_mfma_f32_32x32x16_bf16 v[18:33], v[190:193], v[222:225], v[18:33]
	global_load_dwordx4 v[178:181], v226, s[20:21] offset:896
	global_load_dwordx4 v[194:197], v227, s[4:5] offset:896
	global_load_dwordx4 v[210:213], v228, s[4:5] offset:896
	global_load_dwordx4 v[182:185], v226, s[20:21] offset:928
	global_load_dwordx4 v[198:201], v227, s[4:5] offset:928
	global_load_dwordx4 v[214:217], v228, s[4:5] offset:928
	global_load_dwordx4 v[186:189], v226, s[20:21] offset:960
	global_load_dwordx4 v[202:205], v227, s[4:5] offset:960
	global_load_dwordx4 v[218:221], v228, s[4:5] offset:960
	global_load_dwordx4 v[190:193], v226, s[20:21] offset:992
	global_load_dwordx4 v[206:209], v227, s[4:5] offset:992
	global_load_dwordx4 v[222:225], v228, s[4:5] offset:992
	s_waitcnt vmcnt(45)
	v_mfma_f32_32x32x16_bf16 v[2:17], v[34:37], v[50:53], v[2:17]
	v_mfma_f32_32x32x16_bf16 v[18:33], v[34:37], v[66:69], v[18:33]
	s_waitcnt vmcnt(42)
	v_mfma_f32_32x32x16_bf16 v[2:17], v[38:41], v[54:57], v[2:17]
	v_mfma_f32_32x32x16_bf16 v[18:33], v[38:41], v[70:73], v[18:33]
	s_waitcnt vmcnt(39)
	v_mfma_f32_32x32x16_bf16 v[2:17], v[42:45], v[58:61], v[2:17]
	v_mfma_f32_32x32x16_bf16 v[18:33], v[42:45], v[74:77], v[18:33]
	s_waitcnt vmcnt(36)
	v_mfma_f32_32x32x16_bf16 v[2:17], v[46:49], v[62:65], v[2:17]
	v_mfma_f32_32x32x16_bf16 v[18:33], v[46:49], v[78:81], v[18:33]
	s_waitcnt vmcnt(33)
	v_mfma_f32_32x32x16_bf16 v[2:17], v[82:85], v[98:101], v[2:17]
	v_mfma_f32_32x32x16_bf16 v[18:33], v[82:85], v[114:117], v[18:33]
	s_waitcnt vmcnt(30)
	v_mfma_f32_32x32x16_bf16 v[2:17], v[86:89], v[102:105], v[2:17]
	v_mfma_f32_32x32x16_bf16 v[18:33], v[86:89], v[118:121], v[18:33]
	s_waitcnt vmcnt(27)
	v_mfma_f32_32x32x16_bf16 v[2:17], v[90:93], v[106:109], v[2:17]
	v_mfma_f32_32x32x16_bf16 v[18:33], v[90:93], v[122:125], v[18:33]
	s_waitcnt vmcnt(24)
	v_mfma_f32_32x32x16_bf16 v[2:17], v[94:97], v[110:113], v[2:17]
	v_mfma_f32_32x32x16_bf16 v[18:33], v[94:97], v[126:129], v[18:33]
	s_waitcnt vmcnt(21)
	v_mfma_f32_32x32x16_bf16 v[2:17], v[130:133], v[146:149], v[2:17]
	v_mfma_f32_32x32x16_bf16 v[18:33], v[130:133], v[162:165], v[18:33]
	s_waitcnt vmcnt(18)
	v_mfma_f32_32x32x16_bf16 v[2:17], v[134:137], v[150:153], v[2:17]
	v_mfma_f32_32x32x16_bf16 v[18:33], v[134:137], v[166:169], v[18:33]
	s_waitcnt vmcnt(15)
	v_mfma_f32_32x32x16_bf16 v[2:17], v[138:141], v[154:157], v[2:17]
	v_mfma_f32_32x32x16_bf16 v[18:33], v[138:141], v[170:173], v[18:33]
	s_waitcnt vmcnt(12)
	v_mfma_f32_32x32x16_bf16 v[2:17], v[142:145], v[158:161], v[2:17]
	v_mfma_f32_32x32x16_bf16 v[18:33], v[142:145], v[174:177], v[18:33]
	s_waitcnt vmcnt(9)
	v_mfma_f32_32x32x16_bf16 v[2:17], v[178:181], v[194:197], v[2:17]
	v_mfma_f32_32x32x16_bf16 v[18:33], v[178:181], v[210:213], v[18:33]
	s_waitcnt vmcnt(6)
	v_mfma_f32_32x32x16_bf16 v[2:17], v[182:185], v[198:201], v[2:17]
	v_mfma_f32_32x32x16_bf16 v[18:33], v[182:185], v[214:217], v[18:33]
	s_waitcnt vmcnt(3)
	v_mfma_f32_32x32x16_bf16 v[2:17], v[186:189], v[202:205], v[2:17]
	v_mfma_f32_32x32x16_bf16 v[18:33], v[186:189], v[218:221], v[18:33]
	s_waitcnt vmcnt(0)
	v_mfma_f32_32x32x16_bf16 v[2:17], v[190:193], v[206:209], v[2:17]
	v_mfma_f32_32x32x16_bf16 v[18:33], v[190:193], v[222:225], v[18:33]
	s_nop 15
	s_nop 3
	global_store_dword v229, v2, s[22:23]
	global_store_dword v229, v18, s[22:23] offset:128
	v_add_u32_e32 v231, 0x1000, v229
	global_store_dword v231, v3, s[22:23]
	global_store_dword v231, v19, s[22:23] offset:128
	v_add_u32_e32 v230, 0x2000, v229
	global_store_dword v230, v4, s[22:23]
	global_store_dword v230, v20, s[22:23] offset:128
	v_add_u32_e32 v231, 0x3000, v229
	global_store_dword v231, v5, s[22:23]
	global_store_dword v231, v21, s[22:23] offset:128
	v_add_u32_e32 v230, 0x8000, v229
	global_store_dword v230, v6, s[22:23]
	global_store_dword v230, v22, s[22:23] offset:128
	v_add_u32_e32 v231, 0x9000, v229
	global_store_dword v231, v7, s[22:23]
	global_store_dword v231, v23, s[22:23] offset:128
	v_add_u32_e32 v230, 0xa000, v229
	global_store_dword v230, v8, s[22:23]
	global_store_dword v230, v24, s[22:23] offset:128
	v_add_u32_e32 v231, 0xb000, v229
	global_store_dword v231, v9, s[22:23]
	global_store_dword v231, v25, s[22:23] offset:128
	v_add_u32_e32 v230, 0x10000, v229
	global_store_dword v230, v10, s[22:23]
	global_store_dword v230, v26, s[22:23] offset:128
	v_add_u32_e32 v231, 0x11000, v229
	global_store_dword v231, v11, s[22:23]
	global_store_dword v231, v27, s[22:23] offset:128
	v_add_u32_e32 v230, 0x12000, v229
	global_store_dword v230, v12, s[22:23]
	global_store_dword v230, v28, s[22:23] offset:128
	v_add_u32_e32 v231, 0x13000, v229
	global_store_dword v231, v13, s[22:23]
	global_store_dword v231, v29, s[22:23] offset:128
	v_add_u32_e32 v230, 0x18000, v229
	global_store_dword v230, v14, s[22:23]
	global_store_dword v230, v30, s[22:23] offset:128
	v_add_u32_e32 v231, 0x19000, v229
	global_store_dword v231, v15, s[22:23]
	global_store_dword v231, v31, s[22:23] offset:128
	v_add_u32_e32 v230, 0x1a000, v229
	global_store_dword v230, v16, s[22:23]
	global_store_dword v230, v32, s[22:23] offset:128
	v_add_u32_e32 v231, 0x1b000, v229
	global_store_dword v231, v17, s[22:23]
	global_store_dword v231, v33, s[22:23] offset:128
	s_add_i32 s12, s12, s24
	s_cmpk_lt_i32 s12, 0x200
	s_cbranch_scc1 .Lsg10_unit

.Lsg13_unit:
	s_and_b32 s28, s14, 7
	s_lshr_b32 s29, s14, 3
	s_and_b32 s25, s29, 7
	s_lshr_b32 s29, s29, 3
	s_lshr_b32 s26, s29, 1
	s_and_b32 s27, s29, 1
	s_lshl_b32 s27, s27, 3
	s_add_u32 s27, s27, s28
	s_lshl_b32 s30, s25, 10
	s_lshl_b32 s31, s27, 18
	s_add_u32 s31, s31, s30
	s_lshl_b32 s33, s26, 19
	s_add_u32 s33, s33, s30
	v_add_u32_e32 v226, s31, v232
	v_add_u32_e32 v227, s33, v232
	v_add_u32_e32 v228, 0x40000, v227
	s_lshl_b32 s34, s25, 21
	s_lshl_b32 s35, s27, 17
	s_add_u32 s34, s34, s35
	s_lshl_b32 s35, s26, 8
	s_add_u32 s34, s34, s35
	v_add_u32_e32 v229, s34, v233
	global_load_dwordx4 v[34:37], v226, s[20:21] offset:0
	global_load_dwordx4 v[50:53], v227, s[4:5] offset:0
	global_load_dwordx4 v[66:69], v228, s[4:5] offset:0
	global_load_dwordx4 v[38:41], v226, s[20:21] offset:32
	global_load_dwordx4 v[54:57], v227, s[4:5] offset:32
	global_load_dwordx4 v[70:73], v228, s[4:5] offset:32
	global_load_dwordx4 v[42:45], v226, s[20:21] offset:64
	global_load_dwordx4 v[58:61], v227, s[4:5] offset:64
	global_load_dwordx4 v[74:77], v228, s[4:5] offset:64
	global_load_dwordx4 v[46:49], v226, s[20:21] offset:96
	global_load_dwordx4 v[62:65], v227, s[4:5] offset:96
	global_load_dwordx4 v[78:81], v228, s[4:5] offset:96
	global_load_dwordx4 v[82:85], v226, s[20:21] offset:128
	global_load_dwordx4 v[98:101], v227, s[4:5] offset:128
	global_load_dwordx4 v[114:117], v228, s[4:5] offset:128
	global_load_dwordx4 v[86:89], v226, s[20:21] offset:160
	global_load_dwordx4 v[102:105], v227, s[4:5] offset:160
	global_load_dwordx4 v[118:121], v228, s[4:5] offset:160
	global_load_dwordx4 v[90:93], v226, s[20:21] offset:192
	global_load_dwordx4 v[106:109], v227, s[4:5] offset:192
	global_load_dwordx4 v[122:125], v228, s[4:5] offset:192
	global_load_dwordx4 v[94:97], v226, s[20:21] offset:224
	global_load_dwordx4 v[110:113], v227, s[4:5] offset:224
	global_load_dwordx4 v[126:129], v228, s[4:5] offset:224
	global_load_dwordx4 v[130:133], v226, s[20:21] offset:256
	global_load_dwordx4 v[146:149], v227, s[4:5] offset:256
	global_load_dwordx4 v[162:165], v228, s[4:5] offset:256
	global_load_dwordx4 v[134:137], v226, s[20:21] offset:288
	global_load_dwordx4 v[150:153], v227, s[4:5] offset:288
	global_load_dwordx4 v[166:169], v228, s[4:5] offset:288
	global_load_dwordx4 v[138:141], v226, s[20:21] offset:320
	global_load_dwordx4 v[154:157], v227, s[4:5] offset:320
	global_load_dwordx4 v[170:173], v228, s[4:5] offset:320
	global_load_dwordx4 v[142:145], v226, s[20:21] offset:352
	global_load_dwordx4 v[158:161], v227, s[4:5] offset:352
	global_load_dwordx4 v[174:177], v228, s[4:5] offset:352
	global_load_dwordx4 v[178:181], v226, s[20:21] offset:384
	global_load_dwordx4 v[194:197], v227, s[4:5] offset:384
	global_load_dwordx4 v[210:213], v228, s[4:5] offset:384
	global_load_dwordx4 v[182:185], v226, s[20:21] offset:416
	global_load_dwordx4 v[198:201], v227, s[4:5] offset:416
	global_load_dwordx4 v[214:217], v228, s[4:5] offset:416
	global_load_dwordx4 v[186:189], v226, s[20:21] offset:448
	global_load_dwordx4 v[202:205], v227, s[4:5] offset:448
	global_load_dwordx4 v[218:221], v228, s[4:5] offset:448
	global_load_dwordx4 v[190:193], v226, s[20:21] offset:480
	global_load_dwordx4 v[206:209], v227, s[4:5] offset:480
	global_load_dwordx4 v[222:225], v228, s[4:5] offset:480
	s_waitcnt vmcnt(45)
	v_mfma_f32_32x32x16_bf16 v[2:17], v[34:37], v[50:53], 0
	v_mfma_f32_32x32x16_bf16 v[18:33], v[34:37], v[66:69], 0
	s_waitcnt vmcnt(42)
	v_mfma_f32_32x32x16_bf16 v[2:17], v[38:41], v[54:57], v[2:17]
	v_mfma_f32_32x32x16_bf16 v[18:33], v[38:41], v[70:73], v[18:33]
	s_waitcnt vmcnt(39)
	v_mfma_f32_32x32x16_bf16 v[2:17], v[42:45], v[58:61], v[2:17]
	v_mfma_f32_32x32x16_bf16 v[18:33], v[42:45], v[74:77], v[18:33]
	s_waitcnt vmcnt(36)
	v_mfma_f32_32x32x16_bf16 v[2:17], v[46:49], v[62:65], v[2:17]
	v_mfma_f32_32x32x16_bf16 v[18:33], v[46:49], v[78:81], v[18:33]
	global_load_dwordx4 v[34:37], v226, s[20:21] offset:512
	global_load_dwordx4 v[50:53], v227, s[4:5] offset:512
	global_load_dwordx4 v[66:69], v228, s[4:5] offset:512
	global_load_dwordx4 v[38:41], v226, s[20:21] offset:544
	global_load_dwordx4 v[54:57], v227, s[4:5] offset:544
	global_load_dwordx4 v[70:73], v228, s[4:5] offset:544
	global_load_dwordx4 v[42:45], v226, s[20:21] offset:576
	global_load_dwordx4 v[58:61], v227, s[4:5] offset:576
	global_load_dwordx4 v[74:77], v228, s[4:5] offset:576
	global_load_dwordx4 v[46:49], v226, s[20:21] offset:608
	global_load_dwordx4 v[62:65], v227, s[4:5] offset:608
	global_load_dwordx4 v[78:81], v228, s[4:5] offset:608
	s_waitcnt vmcnt(45)
	v_mfma_f32_32x32x16_bf16 v[2:17], v[82:85], v[98:101], v[2:17]
	v_mfma_f32_32x32x16_bf16 v[18:33], v[82:85], v[114:117], v[18:33]
	s_waitcnt vmcnt(42)
	v_mfma_f32_32x32x16_bf16 v[2:17], v[86:89], v[102:105], v[2:17]
	v_mfma_f32_32x32x16_bf16 v[18:33], v[86:89], v[118:121], v[18:33]
	s_waitcnt vmcnt(39)
	v_mfma_f32_32x32x16_bf16 v[2:17], v[90:93], v[106:109], v[2:17]
	v_mfma_f32_32x32x16_bf16 v[18:33], v[90:93], v[122:125], v[18:33]
	s_waitcnt vmcnt(36)
	v_mfma_f32_32x32x16_bf16 v[2:17], v[94:97], v[110:113], v[2:17]
	v_mfma_f32_32x32x16_bf16 v[18:33], v[94:97], v[126:129], v[18:33]
	global_load_dwordx4 v[82:85], v226, s[20:21] offset:640
	global_load_dwordx4 v[98:101], v227, s[4:5] offset:640
	global_load_dwordx4 v[114:117], v228, s[4:5] offset:640
	global_load_dwordx4 v[86:89], v226, s[20:21] offset:672
	global_load_dwordx4 v[102:105], v227, s[4:5] offset:672
	global_load_dwordx4 v[118:121], v228, s[4:5] offset:672
	global_load_dwordx4 v[90:93], v226, s[20:21] offset:704
	global_load_dwordx4 v[106:109], v227, s[4:5] offset:704
	global_load_dwordx4 v[122:125], v228, s[4:5] offset:704
	global_load_dwordx4 v[94:97], v226, s[20:21] offset:736
	global_load_dwordx4 v[110:113], v227, s[4:5] offset:736
	global_load_dwordx4 v[126:129], v228, s[4:5] offset:736
	s_waitcnt vmcnt(45)
	v_mfma_f32_32x32x16_bf16 v[2:17], v[130:133], v[146:149], v[2:17]
	v_mfma_f32_32x32x16_bf16 v[18:33], v[130:133], v[162:165], v[18:33]
	s_waitcnt vmcnt(42)
	v_mfma_f32_32x32x16_bf16 v[2:17], v[134:137], v[150:153], v[2:17]
	v_mfma_f32_32x32x16_bf16 v[18:33], v[134:137], v[166:169], v[18:33]
	s_waitcnt vmcnt(39)
	v_mfma_f32_32x32x16_bf16 v[2:17], v[138:141], v[154:157], v[2:17]
	v_mfma_f32_32x32x16_bf16 v[18:33], v[138:141], v[170:173], v[18:33]
	s_waitcnt vmcnt(36)
	v_mfma_f32_32x32x16_bf16 v[2:17], v[142:145], v[158:161], v[2:17]
	v_mfma_f32_32x32x16_bf16 v[18:33], v[142:145], v[174:177], v[18:33]
	global_load_dwordx4 v[130:133], v226, s[20:21] offset:768
	global_load_dwordx4 v[146:149], v227, s[4:5] offset:768
	global_load_dwordx4 v[162:165], v228, s[4:5] offset:768
	global_load_dwordx4 v[134:137], v226, s[20:21] offset:800
	global_load_dwordx4 v[150:153], v227, s[4:5] offset:800
	global_load_dwordx4 v[166:169], v228, s[4:5] offset:800
	global_load_dwordx4 v[138:141], v226, s[20:21] offset:832
	global_load_dwordx4 v[154:157], v227, s[4:5] offset:832
	global_load_dwordx4 v[170:173], v228, s[4:5] offset:832
	global_load_dwordx4 v[142:145], v226, s[20:21] offset:864
	global_load_dwordx4 v[158:161], v227, s[4:5] offset:864
	global_load_dwordx4 v[174:177], v228, s[4:5] offset:864
	s_waitcnt vmcnt(45)
	v_mfma_f32_32x32x16_bf16 v[2:17], v[178:181], v[194:197], v[2:17]
	v_mfma_f32_32x32x16_bf16 v[18:33], v[178:181], v[210:213], v[18:33]
	s_waitcnt vmcnt(42)
	v_mfma_f32_32x32x16_bf16 v[2:17], v[182:185], v[198:201], v[2:17]
	v_mfma_f32_32x32x16_bf16 v[18:33], v[182:185], v[214:217], v[18:33]
	s_waitcnt vmcnt(39)
	v_mfma_f32_32x32x16_bf16 v[2:17], v[186:189], v[202:205], v[2:17]
	v_mfma_f32_32x32x16_bf16 v[18:33], v[186:189], v[218:221], v[18:33]
	s_waitcnt vmcnt(36)
	v_mfma_f32_32x32x16_bf16 v[2:17], v[190:193], v[206:209], v[2:17]
	v_mfma_f32_32x32x16_bf16 v[18:33], v[190:193], v[222:225], v[18:33]
	global_load_dwordx4 v[178:181], v226, s[20:21] offset:896
	global_load_dwordx4 v[194:197], v227, s[4:5] offset:896
	global_load_dwordx4 v[210:213], v228, s[4:5] offset:896
	global_load_dwordx4 v[182:185], v226, s[20:21] offset:928
	global_load_dwordx4 v[198:201], v227, s[4:5] offset:928
	global_load_dwordx4 v[214:217], v228, s[4:5] offset:928
	global_load_dwordx4 v[186:189], v226, s[20:21] offset:960
	global_load_dwordx4 v[202:205], v227, s[4:5] offset:960
	global_load_dwordx4 v[218:221], v228, s[4:5] offset:960
	global_load_dwordx4 v[190:193], v226, s[20:21] offset:992
	global_load_dwordx4 v[206:209], v227, s[4:5] offset:992
	global_load_dwordx4 v[222:225], v228, s[4:5] offset:992
	s_waitcnt vmcnt(45)
	v_mfma_f32_32x32x16_bf16 v[2:17], v[34:37], v[50:53], v[2:17]
	v_mfma_f32_32x32x16_bf16 v[18:33], v[34:37], v[66:69], v[18:33]
	s_waitcnt vmcnt(42)
	v_mfma_f32_32x32x16_bf16 v[2:17], v[38:41], v[54:57], v[2:17]
	v_mfma_f32_32x32x16_bf16 v[18:33], v[38:41], v[70:73], v[18:33]
	s_waitcnt vmcnt(39)
	v_mfma_f32_32x32x16_bf16 v[2:17], v[42:45], v[58:61], v[2:17]
	v_mfma_f32_32x32x16_bf16 v[18:33], v[42:45], v[74:77], v[18:33]
	s_waitcnt vmcnt(36)
	v_mfma_f32_32x32x16_bf16 v[2:17], v[46:49], v[62:65], v[2:17]
	v_mfma_f32_32x32x16_bf16 v[18:33], v[46:49], v[78:81], v[18:33]
	s_waitcnt vmcnt(33)
	v_mfma_f32_32x32x16_bf16 v[2:17], v[82:85], v[98:101], v[2:17]
	v_mfma_f32_32x32x16_bf16 v[18:33], v[82:85], v[114:117], v[18:33]
	s_waitcnt vmcnt(30)
	v_mfma_f32_32x32x16_bf16 v[2:17], v[86:89], v[102:105], v[2:17]
	v_mfma_f32_32x32x16_bf16 v[18:33], v[86:89], v[118:121], v[18:33]
	s_waitcnt vmcnt(27)
	v_mfma_f32_32x32x16_bf16 v[2:17], v[90:93], v[106:109], v[2:17]
	v_mfma_f32_32x32x16_bf16 v[18:33], v[90:93], v[122:125], v[18:33]
	s_waitcnt vmcnt(24)
	v_mfma_f32_32x32x16_bf16 v[2:17], v[94:97], v[110:113], v[2:17]
	v_mfma_f32_32x32x16_bf16 v[18:33], v[94:97], v[126:129], v[18:33]
	s_waitcnt vmcnt(21)
	v_mfma_f32_32x32x16_bf16 v[2:17], v[130:133], v[146:149], v[2:17]
	v_mfma_f32_32x32x16_bf16 v[18:33], v[130:133], v[162:165], v[18:33]
	s_waitcnt vmcnt(18)
	v_mfma_f32_32x32x16_bf16 v[2:17], v[134:137], v[150:153], v[2:17]
	v_mfma_f32_32x32x16_bf16 v[18:33], v[134:137], v[166:169], v[18:33]
	s_waitcnt vmcnt(15)
	v_mfma_f32_32x32x16_bf16 v[2:17], v[138:141], v[154:157], v[2:17]
	v_mfma_f32_32x32x16_bf16 v[18:33], v[138:141], v[170:173], v[18:33]
	s_waitcnt vmcnt(12)
	v_mfma_f32_32x32x16_bf16 v[2:17], v[142:145], v[158:161], v[2:17]
	v_mfma_f32_32x32x16_bf16 v[18:33], v[142:145], v[174:177], v[18:33]
	s_waitcnt vmcnt(9)
	v_mfma_f32_32x32x16_bf16 v[2:17], v[178:181], v[194:197], v[2:17]
	v_mfma_f32_32x32x16_bf16 v[18:33], v[178:181], v[210:213], v[18:33]
	s_waitcnt vmcnt(6)
	v_mfma_f32_32x32x16_bf16 v[2:17], v[182:185], v[198:201], v[2:17]
	v_mfma_f32_32x32x16_bf16 v[18:33], v[182:185], v[214:217], v[18:33]
	s_waitcnt vmcnt(3)
	v_mfma_f32_32x32x16_bf16 v[2:17], v[186:189], v[202:205], v[2:17]
	v_mfma_f32_32x32x16_bf16 v[18:33], v[186:189], v[218:221], v[18:33]
	s_waitcnt vmcnt(0)
	v_mfma_f32_32x32x16_bf16 v[2:17], v[190:193], v[206:209], v[2:17]
	v_mfma_f32_32x32x16_bf16 v[18:33], v[190:193], v[222:225], v[18:33]
	s_nop 15
	s_nop 3
	global_store_dword v229, v2, s[22:23]
	global_store_dword v229, v18, s[22:23] offset:128
	v_add_u32_e32 v231, 0x1000, v229
	global_store_dword v231, v3, s[22:23]
	global_store_dword v231, v19, s[22:23] offset:128
	v_add_u32_e32 v230, 0x2000, v229
	global_store_dword v230, v4, s[22:23]
	global_store_dword v230, v20, s[22:23] offset:128
	v_add_u32_e32 v231, 0x3000, v229
	global_store_dword v231, v5, s[22:23]
	global_store_dword v231, v21, s[22:23] offset:128
	v_add_u32_e32 v230, 0x8000, v229
	global_store_dword v230, v6, s[22:23]
	global_store_dword v230, v22, s[22:23] offset:128
	v_add_u32_e32 v231, 0x9000, v229
	global_store_dword v231, v7, s[22:23]
	global_store_dword v231, v23, s[22:23] offset:128
	v_add_u32_e32 v230, 0xa000, v229
	global_store_dword v230, v8, s[22:23]
	global_store_dword v230, v24, s[22:23] offset:128
	v_add_u32_e32 v231, 0xb000, v229
	global_store_dword v231, v9, s[22:23]
	global_store_dword v231, v25, s[22:23] offset:128
	v_add_u32_e32 v230, 0x10000, v229
	global_store_dword v230, v10, s[22:23]
	global_store_dword v230, v26, s[22:23] offset:128
	v_add_u32_e32 v231, 0x11000, v229
	global_store_dword v231, v11, s[22:23]
	global_store_dword v231, v27, s[22:23] offset:128
	v_add_u32_e32 v230, 0x12000, v229
	global_store_dword v230, v12, s[22:23]
	global_store_dword v230, v28, s[22:23] offset:128
	v_add_u32_e32 v231, 0x13000, v229
	global_store_dword v231, v13, s[22:23]
	global_store_dword v231, v29, s[22:23] offset:128
	v_add_u32_e32 v230, 0x18000, v229
	global_store_dword v230, v14, s[22:23]
	global_store_dword v230, v30, s[22:23] offset:128
	v_add_u32_e32 v231, 0x19000, v229
	global_store_dword v231, v15, s[22:23]
	global_store_dword v231, v31, s[22:23] offset:128
	v_add_u32_e32 v230, 0x1a000, v229
	global_store_dword v230, v16, s[22:23]
	global_store_dword v230, v32, s[22:23] offset:128
	v_add_u32_e32 v231, 0x1b000, v229
	global_store_dword v231, v17, s[22:23]
	global_store_dword v231, v33, s[22:23] offset:128
	s_add_i32 s14, s14, s24
	s_cmpk_lt_i32 s14, 0x800
	s_cbranch_scc1 .Lsg13_unit

amdhsa.kernels:
  - .agpr_count:     0
    .args:
      - .offset:         0
        .size:           232
        .value_kind:     by_value
      - .offset:         232
        .size:           4
        .value_kind:     hidden_block_count_x
      - .offset:         236
        .size:           4
        .value_kind:     hidden_block_count_y
      - .offset:         240
        .size:           4
        .value_kind:     hidden_block_count_z
      - .offset:         244
        .size:           2
        .value_kind:     hidden_group_size_x
      - .offset:         246
        .size:           2
        .value_kind:     hidden_group_size_y
      - .offset:         248
        .size:           2
        .value_kind:     hidden_group_size_z
      - .offset:         250
        .size:           2
        .value_kind:     hidden_remainder_x
      - .offset:         252
        .size:           2
        .value_kind:     hidden_remainder_y
      - .offset:         254
        .size:           2
        .value_kind:     hidden_remainder_z
      - .offset:         272
        .size:           8
        .value_kind:     hidden_global_offset_x
      - .offset:         280
        .size:           8
        .value_kind:     hidden_global_offset_y
      - .offset:         288
        .size:           8
        .value_kind:     hidden_global_offset_z
      - .offset:         296
        .size:           2
        .value_kind:     hidden_grid_dims
      - .offset:         352
        .size:           4
        .value_kind:     hidden_dynamic_lds_size
    .group_segment_fixed_size: 0
    .kernarg_segment_align: 8
    .kernarg_segment_size: 488
    .language:       OpenCL C
    .language_version:
      - 2
      - 0
    .max_flat_workgroup_size: 512
    .name:           _Z10fwd_kernelILi0ELi1EEv4Args
    .private_segment_fixed_size: 0
    .sgpr_count:     106
    .sgpr_spill_count: 0
    .symbol:         _Z10fwd_kernelILi0ELi1EEv4Args.kd
    .uniform_work_group_size: 1
    .uses_dynamic_stack: false
    .vgpr_count:     224
    .vgpr_spill_count: 0
    .wavefront_size: 64
  - .agpr_count:     0
    .args:
      - .offset:         0
        .size:           232
        .value_kind:     by_value
      - .offset:         232
        .size:           4
        .value_kind:     hidden_block_count_x
      - .offset:         236
        .size:           4
        .value_kind:     hidden_block_count_y
      - .offset:         240
        .size:           4
        .value_kind:     hidden_block_count_z
      - .offset:         244
        .size:           2
        .value_kind:     hidden_group_size_x
      - .offset:         246
        .size:           2
        .value_kind:     hidden_group_size_y
      - .offset:         248
        .size:           2
        .value_kind:     hidden_group_size_z
      - .offset:         250
        .size:           2
        .value_kind:     hidden_remainder_x
      - .offset:         252
        .size:           2
        .value_kind:     hidden_remainder_y
      - .offset:         254
        .size:           2
        .value_kind:     hidden_remainder_z
      - .offset:         272
        .size:           8
        .value_kind:     hidden_global_offset_x
      - .offset:         280
        .size:           8
        .value_kind:     hidden_global_offset_y
      - .offset:         288
        .size:           8
        .value_kind:     hidden_global_offset_z
      - .offset:         296
        .size:           2
        .value_kind:     hidden_grid_dims
      - .offset:         352
        .size:           4
        .value_kind:     hidden_dynamic_lds_size
    .group_segment_fixed_size: 0
    .kernarg_segment_align: 8
    .kernarg_segment_size: 488
    .language:       OpenCL C
    .language_version:
      - 2
      - 0
    .max_flat_workgroup_size: 512
    .name:           _Z10fwd_kernelILi1ELi2EEv4Args
    .private_segment_fixed_size: 0
    .sgpr_count:     64
    .sgpr_spill_count: 0
    .symbol:         _Z10fwd_kernelILi1ELi2EEv4Args.kd
    .uniform_work_group_size: 1
    .uses_dynamic_stack: false
    .vgpr_count:     226
    .vgpr_spill_count: 0
    .wavefront_size: 64
  - .agpr_count:     0
    .args:
      - .offset:         0
        .size:           232
        .value_kind:     by_value
      - .offset:         232
        .size:           4
        .value_kind:     hidden_block_count_x
      - .offset:         236
        .size:           4
        .value_kind:     hidden_block_count_y
      - .offset:         240
        .size:           4
        .value_kind:     hidden_block_count_z
      - .offset:         244
        .size:           2
        .value_kind:     hidden_group_size_x
      - .offset:         246
        .size:           2
        .value_kind:     hidden_group_size_y
      - .offset:         248
        .size:           2
        .value_kind:     hidden_group_size_z
      - .offset:         250
        .size:           2
        .value_kind:     hidden_remainder_x
      - .offset:         252
        .size:           2
        .value_kind:     hidden_remainder_y
      - .offset:         254
        .size:           2
        .value_kind:     hidden_remainder_z
      - .offset:         272
        .size:           8
        .value_kind:     hidden_global_offset_x
      - .offset:         280
        .size:           8
        .value_kind:     hidden_global_offset_y
      - .offset:         288
        .size:           8
        .value_kind:     hidden_global_offset_z
      - .offset:         296
        .size:           2
        .value_kind:     hidden_grid_dims
      - .offset:         352
        .size:           4
        .value_kind:     hidden_dynamic_lds_size
    .group_segment_fixed_size: 0
    .kernarg_segment_align: 8
    .kernarg_segment_size: 488
    .language:       OpenCL C
    .language_version:
      - 2
      - 0
    .max_flat_workgroup_size: 512
    .name:           _Z10fwd_kernelILi2ELi3EEv4Args
    .private_segment_fixed_size: 0
    .sgpr_count:     106
    .sgpr_spill_count: 11
    .symbol:         _Z10fwd_kernelILi2ELi3EEv4Args.kd
    .uniform_work_group_size: 1
    .uses_dynamic_stack: false
    .vgpr_count:     252
    .vgpr_spill_count: 0
    .wavefront_size: 64
  - .agpr_count:     0
    .args:
      - .offset:         0
        .size:           232
        .value_kind:     by_value
      - .offset:         232
        .size:           4
        .value_kind:     hidden_block_count_x
      - .offset:         236
        .size:           4
        .value_kind:     hidden_block_count_y
      - .offset:         240
        .size:           4
        .value_kind:     hidden_block_count_z
      - .offset:         244
        .size:           2
        .value_kind:     hidden_group_size_x
      - .offset:         246
        .size:           2
        .value_kind:     hidden_group_size_y
      - .offset:         248
        .size:           2
        .value_kind:     hidden_group_size_z
      - .offset:         250
        .size:           2
        .value_kind:     hidden_remainder_x
      - .offset:         252
        .size:           2
        .value_kind:     hidden_remainder_y
      - .offset:         254
        .size:           2
        .value_kind:     hidden_remainder_z
      - .offset:         272
        .size:           8
        .value_kind:     hidden_global_offset_x
      - .offset:         280
        .size:           8
        .value_kind:     hidden_global_offset_y
      - .offset:         288
        .size:           8
        .value_kind:     hidden_global_offset_z
      - .offset:         296
        .size:           2
        .value_kind:     hidden_grid_dims
      - .offset:         352
        .size:           4
        .value_kind:     hidden_dynamic_lds_size
    .group_segment_fixed_size: 0
    .kernarg_segment_align: 8
    .kernarg_segment_size: 488
    .language:       OpenCL C
    .language_version:
      - 2
      - 0
    .max_flat_workgroup_size: 512
    .name:           _Z10fwd_kernelILi3ELi4EEv4Args
    .private_segment_fixed_size: 0
    .sgpr_count:     67
    .sgpr_spill_count: 0
    .symbol:         _Z10fwd_kernelILi3ELi4EEv4Args.kd
    .uniform_work_group_size: 1
    .uses_dynamic_stack: false
    .vgpr_count:     240
    .vgpr_spill_count: 0
    .wavefront_size: 64
  - .agpr_count:     0
    .args:
      - .offset:         0
        .size:           232
        .value_kind:     by_value
      - .offset:         232
        .size:           4
        .value_kind:     hidden_block_count_x
      - .offset:         236
        .size:           4
        .value_kind:     hidden_block_count_y
      - .offset:         240
        .size:           4
        .value_kind:     hidden_block_count_z
      - .offset:         244
        .size:           2
        .value_kind:     hidden_group_size_x
      - .offset:         246
        .size:           2
        .value_kind:     hidden_group_size_y
      - .offset:         248
        .size:           2
        .value_kind:     hidden_group_size_z
      - .offset:         250
        .size:           2
        .value_kind:     hidden_remainder_x
      - .offset:         252
        .size:           2
        .value_kind:     hidden_remainder_y
      - .offset:         254
        .size:           2
        .value_kind:     hidden_remainder_z
      - .offset:         272
        .size:           8
        .value_kind:     hidden_global_offset_x
      - .offset:         280
        .size:           8
        .value_kind:     hidden_global_offset_y
      - .offset:         288
        .size:           8
        .value_kind:     hidden_global_offset_z
      - .offset:         296
        .size:           2
        .value_kind:     hidden_grid_dims
    .group_segment_fixed_size: 0
    .kernarg_segment_align: 8
    .kernarg_segment_size: 488
    .language:       OpenCL C
    .language_version:
      - 2
      - 0
    .max_flat_workgroup_size: 512
    .name:           _Z10fwd_kernelILi4ELi5EEv4Args
    .private_segment_fixed_size: 0
    .sgpr_count:     62
    .sgpr_spill_count: 0
    .symbol:         _Z10fwd_kernelILi4ELi5EEv4Args.kd
    .uniform_work_group_size: 1
    .uses_dynamic_stack: false
    .vgpr_count:     208
    .vgpr_spill_count: 0
    .wavefront_size: 64
  - .agpr_count:     0
    .args:
      - .offset:         0
        .size:           232
        .value_kind:     by_value
      - .offset:         232
        .size:           4
        .value_kind:     hidden_block_count_x
      - .offset:         236
        .size:           4
        .value_kind:     hidden_block_count_y
      - .offset:         240
        .size:           4
        .value_kind:     hidden_block_count_z
      - .offset:         244
        .size:           2
        .value_kind:     hidden_group_size_x
      - .offset:         246
        .size:           2
        .value_kind:     hidden_group_size_y
      - .offset:         248
        .size:           2
        .value_kind:     hidden_group_size_z
      - .offset:         250
        .size:           2
        .value_kind:     hidden_remainder_x
      - .offset:         252
        .size:           2
        .value_kind:     hidden_remainder_y
      - .offset:         254
        .size:           2
        .value_kind:     hidden_remainder_z
      - .offset:         272
        .size:           8
        .value_kind:     hidden_global_offset_x
      - .offset:         280
        .size:           8
        .value_kind:     hidden_global_offset_y
      - .offset:         288
        .size:           8
        .value_kind:     hidden_global_offset_z
      - .offset:         296
        .size:           2
        .value_kind:     hidden_grid_dims
      - .offset:         352
        .size:           4
        .value_kind:     hidden_dynamic_lds_size
    .group_segment_fixed_size: 0
    .kernarg_segment_align: 8
    .kernarg_segment_size: 488
    .language:       OpenCL C
    .language_version:
      - 2
      - 0
    .max_flat_workgroup_size: 512
    .name:           _Z10fwd_kernelILi5ELi6EEv4Args
    .private_segment_fixed_size: 0
    .sgpr_count:     68
    .sgpr_spill_count: 0
    .symbol:         _Z10fwd_kernelILi5ELi6EEv4Args.kd
    .uniform_work_group_size: 1
    .uses_dynamic_stack: false
    .vgpr_count:     224
    .vgpr_spill_count: 0
    .wavefront_size: 64
  - .agpr_count:     0
    .args:
      - .offset:         0
        .size:           232
        .value_kind:     by_value
      - .offset:         232
        .size:           4
        .value_kind:     hidden_block_count_x
      - .offset:         236
        .size:           4
        .value_kind:     hidden_block_count_y
      - .offset:         240
        .size:           4
        .value_kind:     hidden_block_count_z
      - .offset:         244
        .size:           2
        .value_kind:     hidden_group_size_x
      - .offset:         246
        .size:           2
        .value_kind:     hidden_group_size_y
      - .offset:         248
        .size:           2
        .value_kind:     hidden_group_size_z
      - .offset:         250
        .size:           2
        .value_kind:     hidden_remainder_x
      - .offset:         252
        .size:           2
        .value_kind:     hidden_remainder_y
      - .offset:         254
        .size:           2
        .value_kind:     hidden_remainder_z
      - .offset:         272
        .size:           8
        .value_kind:     hidden_global_offset_x
      - .offset:         280
        .size:           8
        .value_kind:     hidden_global_offset_y
      - .offset:         288
        .size:           8
        .value_kind:     hidden_global_offset_z
      - .offset:         296
        .size:           2
        .value_kind:     hidden_grid_dims
      - .offset:         352
        .size:           4
        .value_kind:     hidden_dynamic_lds_size
    .group_segment_fixed_size: 0
    .kernarg_segment_align: 8
    .kernarg_segment_size: 488
    .language:       OpenCL C
    .language_version:
      - 2
      - 0
    .max_flat_workgroup_size: 512
    .name:           _Z10fwd_kernelILi6ELi7EEv4Args
    .private_segment_fixed_size: 0
    .sgpr_count:     67
    .sgpr_spill_count: 0
    .symbol:         _Z10fwd_kernelILi6ELi7EEv4Args.kd
    .uniform_work_group_size: 1
    .uses_dynamic_stack: false
    .vgpr_count:     240
    .vgpr_spill_count: 0
    .wavefront_size: 64
  - .agpr_count:     0
    .args:
      - .offset:         0
        .size:           232
        .value_kind:     by_value
      - .offset:         232
        .size:           4
        .value_kind:     hidden_block_count_x
      - .offset:         236
        .size:           4
        .value_kind:     hidden_block_count_y
      - .offset:         240
        .size:           4
        .value_kind:     hidden_block_count_z
      - .offset:         244
        .size:           2
        .value_kind:     hidden_group_size_x
      - .offset:         246
        .size:           2
        .value_kind:     hidden_group_size_y
      - .offset:         248
        .size:           2
        .value_kind:     hidden_group_size_z
      - .offset:         250
        .size:           2
        .value_kind:     hidden_remainder_x
      - .offset:         252
        .size:           2
        .value_kind:     hidden_remainder_y
      - .offset:         254
        .size:           2
        .value_kind:     hidden_remainder_z
      - .offset:         272
        .size:           8
        .value_kind:     hidden_global_offset_x
      - .offset:         280
        .size:           8
        .value_kind:     hidden_global_offset_y
      - .offset:         288
        .size:           8
        .value_kind:     hidden_global_offset_z
      - .offset:         296
        .size:           2
        .value_kind:     hidden_grid_dims
    .group_segment_fixed_size: 0
    .kernarg_segment_align: 8
    .kernarg_segment_size: 488
    .language:       OpenCL C
    .language_version:
      - 2
      - 0
    .max_flat_workgroup_size: 512
    .name:           _Z10fwd_kernelILi7ELi8EEv4Args
    .private_segment_fixed_size: 0
    .sgpr_count:     62
    .sgpr_spill_count: 0
    .symbol:         _Z10fwd_kernelILi7ELi8EEv4Args.kd
    .uniform_work_group_size: 1
    .uses_dynamic_stack: false
    .vgpr_count:     208
    .vgpr_spill_count: 0
    .wavefront_size: 64
  - .agpr_count:     0
    .args:
      - .offset:         0
        .size:           232
        .value_kind:     by_value
      - .offset:         232
        .size:           4
        .value_kind:     hidden_block_count_x
      - .offset:         236
        .size:           4
        .value_kind:     hidden_block_count_y
      - .offset:         240
        .size:           4
        .value_kind:     hidden_block_count_z
      - .offset:         244
        .size:           2
        .value_kind:     hidden_group_size_x
      - .offset:         246
        .size:           2
        .value_kind:     hidden_group_size_y
      - .offset:         248
        .size:           2
        .value_kind:     hidden_group_size_z
      - .offset:         250
        .size:           2
        .value_kind:     hidden_remainder_x
      - .offset:         252
        .size:           2
        .value_kind:     hidden_remainder_y
      - .offset:         254
        .size:           2
        .value_kind:     hidden_remainder_z
      - .offset:         272
        .size:           8
        .value_kind:     hidden_global_offset_x
      - .offset:         280
        .size:           8
        .value_kind:     hidden_global_offset_y
      - .offset:         288
        .size:           8
        .value_kind:     hidden_global_offset_z
      - .offset:         296
        .size:           2
        .value_kind:     hidden_grid_dims
      - .offset:         352
        .size:           4
        .value_kind:     hidden_dynamic_lds_size
    .group_segment_fixed_size: 0
    .kernarg_segment_align: 8
    .kernarg_segment_size: 488
    .language:       OpenCL C
    .language_version:
      - 2
      - 0
    .max_flat_workgroup_size: 512
    .name:           _Z10fwd_kernelILi8ELi9EEv4Args
    .private_segment_fixed_size: 0
    .sgpr_count:     75
    .sgpr_spill_count: 0
    .symbol:         _Z10fwd_kernelILi8ELi9EEv4Args.kd
    .uniform_work_group_size: 1
    .uses_dynamic_stack: false
    .vgpr_count:     226
    .vgpr_spill_count: 0
    .wavefront_size: 64
  - .agpr_count:     0
    .args:
      - .offset:         0
        .size:           232
        .value_kind:     by_value
      - .offset:         232
        .size:           4
        .value_kind:     hidden_block_count_x
      - .offset:         236
        .size:           4
        .value_kind:     hidden_block_count_y
      - .offset:         240
        .size:           4
        .value_kind:     hidden_block_count_z
      - .offset:         244
        .size:           2
        .value_kind:     hidden_group_size_x
      - .offset:         246
        .size:           2
        .value_kind:     hidden_group_size_y
      - .offset:         248
        .size:           2
        .value_kind:     hidden_group_size_z
      - .offset:         250
        .size:           2
        .value_kind:     hidden_remainder_x
      - .offset:         252
        .size:           2
        .value_kind:     hidden_remainder_y
      - .offset:         254
        .size:           2
        .value_kind:     hidden_remainder_z
      - .offset:         272
        .size:           8
        .value_kind:     hidden_global_offset_x
      - .offset:         280
        .size:           8
        .value_kind:     hidden_global_offset_y
      - .offset:         288
        .size:           8
        .value_kind:     hidden_global_offset_z
      - .offset:         296
        .size:           2
        .value_kind:     hidden_grid_dims
      - .offset:         352
        .size:           4
        .value_kind:     hidden_dynamic_lds_size
    .group_segment_fixed_size: 0
    .kernarg_segment_align: 8
    .kernarg_segment_size: 488
    .language:       OpenCL C
    .language_version:
      - 2
      - 0
    .max_flat_workgroup_size: 512
    .name:           _Z10fwd_kernelILi9ELi10EEv4Args
    .private_segment_fixed_size: 0
    .sgpr_count:     82
    .sgpr_spill_count: 0
    .symbol:         _Z10fwd_kernelILi9ELi10EEv4Args.kd
    .uniform_work_group_size: 1
    .uses_dynamic_stack: false
    .vgpr_count:     174
    .vgpr_spill_count: 0
    .wavefront_size: 64
  - .agpr_count:     0
    .args:
      - .offset:         0
        .size:           232
        .value_kind:     by_value
      - .offset:         232
        .size:           4
        .value_kind:     hidden_block_count_x
      - .offset:         236
        .size:           4
        .value_kind:     hidden_block_count_y
      - .offset:         240
        .size:           4
        .value_kind:     hidden_block_count_z
      - .offset:         244
        .size:           2
        .value_kind:     hidden_group_size_x
      - .offset:         246
        .size:           2
        .value_kind:     hidden_group_size_y
      - .offset:         248
        .size:           2
        .value_kind:     hidden_group_size_z
      - .offset:         250
        .size:           2
        .value_kind:     hidden_remainder_x
      - .offset:         252
        .size:           2
        .value_kind:     hidden_remainder_y
      - .offset:         254
        .size:           2
        .value_kind:     hidden_remainder_z
      - .offset:         272
        .size:           8
        .value_kind:     hidden_global_offset_x
      - .offset:         280
        .size:           8
        .value_kind:     hidden_global_offset_y
      - .offset:         288
        .size:           8
        .value_kind:     hidden_global_offset_z
      - .offset:         296
        .size:           2
        .value_kind:     hidden_grid_dims
      - .offset:         352
        .size:           4
        .value_kind:     hidden_dynamic_lds_size
    .group_segment_fixed_size: 0
    .kernarg_segment_align: 8
    .kernarg_segment_size: 488
    .language:       OpenCL C
    .language_version:
      - 2
      - 0
    .max_flat_workgroup_size: 512
    .name:           _Z10fwd_kernelILi10ELi11EEv4Args
    .private_segment_fixed_size: 0
    .sgpr_count:     67
    .sgpr_spill_count: 0
    .symbol:         _Z10fwd_kernelILi10ELi11EEv4Args.kd
    .uniform_work_group_size: 1
    .uses_dynamic_stack: false
    .vgpr_count:     240
    .vgpr_spill_count: 0
    .wavefront_size: 64
  - .agpr_count:     0
    .args:
      - .offset:         0
        .size:           232
        .value_kind:     by_value
      - .offset:         232
        .size:           4
        .value_kind:     hidden_block_count_x
      - .offset:         236
        .size:           4
        .value_kind:     hidden_block_count_y
      - .offset:         240
        .size:           4
        .value_kind:     hidden_block_count_z
      - .offset:         244
        .size:           2
        .value_kind:     hidden_group_size_x
      - .offset:         246
        .size:           2
        .value_kind:     hidden_group_size_y
      - .offset:         248
        .size:           2
        .value_kind:     hidden_group_size_z
      - .offset:         250
        .size:           2
        .value_kind:     hidden_remainder_x
      - .offset:         252
        .size:           2
        .value_kind:     hidden_remainder_y
      - .offset:         254
        .size:           2
        .value_kind:     hidden_remainder_z
      - .offset:         272
        .size:           8
        .value_kind:     hidden_global_offset_x
      - .offset:         280
        .size:           8
        .value_kind:     hidden_global_offset_y
      - .offset:         288
        .size:           8
        .value_kind:     hidden_global_offset_z
      - .offset:         296
        .size:           2
        .value_kind:     hidden_grid_dims
    .group_segment_fixed_size: 0
    .kernarg_segment_align: 8
    .kernarg_segment_size: 488
    .language:       OpenCL C
    .language_version:
      - 2
      - 0
    .max_flat_workgroup_size: 512
    .name:           _Z10fwd_kernelILi11ELi12EEv4Args
    .private_segment_fixed_size: 0
    .sgpr_count:     62
    .sgpr_spill_count: 0
    .symbol:         _Z10fwd_kernelILi11ELi12EEv4Args.kd
    .uniform_work_group_size: 1
    .uses_dynamic_stack: false
    .vgpr_count:     208
    .vgpr_spill_count: 0
    .wavefront_size: 64
  - .agpr_count:     0
    .args:
      - .offset:         0
        .size:           232
        .value_kind:     by_value
      - .offset:         232
        .size:           4
        .value_kind:     hidden_block_count_x
      - .offset:         236
        .size:           4
        .value_kind:     hidden_block_count_y
      - .offset:         240
        .size:           4
        .value_kind:     hidden_block_count_z
      - .offset:         244
        .size:           2
        .value_kind:     hidden_group_size_x
      - .offset:         246
        .size:           2
        .value_kind:     hidden_group_size_y
      - .offset:         248
        .size:           2
        .value_kind:     hidden_group_size_z
      - .offset:         250
        .size:           2
        .value_kind:     hidden_remainder_x
      - .offset:         252
        .size:           2
        .value_kind:     hidden_remainder_y
      - .offset:         254
        .size:           2
        .value_kind:     hidden_remainder_z
      - .offset:         272
        .size:           8
        .value_kind:     hidden_global_offset_x
      - .offset:         280
        .size:           8
        .value_kind:     hidden_global_offset_y
      - .offset:         288
        .size:           8
        .value_kind:     hidden_global_offset_z
      - .offset:         296
        .size:           2
        .value_kind:     hidden_grid_dims
      - .offset:         352
        .size:           4
        .value_kind:     hidden_dynamic_lds_size
    .group_segment_fixed_size: 0
    .kernarg_segment_align: 8
    .kernarg_segment_size: 488
    .language:       OpenCL C
    .language_version:
      - 2
      - 0
    .max_flat_workgroup_size: 512
    .name:           _Z10fwd_kernelILi12ELi13EEv4Args
    .private_segment_fixed_size: 0
    .sgpr_count:     68
    .sgpr_spill_count: 0
    .symbol:         _Z10fwd_kernelILi12ELi13EEv4Args.kd
    .uniform_work_group_size: 1
    .uses_dynamic_stack: false
    .vgpr_count:     224
    .vgpr_spill_count: 0
    .wavefront_size: 64
  - .agpr_count:     0
    .args:
      - .offset:         0
        .size:           232
        .value_kind:     by_value
      - .offset:         232
        .size:           4
        .value_kind:     hidden_block_count_x
      - .offset:         236
        .size:           4
        .value_kind:     hidden_block_count_y
      - .offset:         240
        .size:           4
        .value_kind:     hidden_block_count_z
      - .offset:         244
        .size:           2
        .value_kind:     hidden_group_size_x
      - .offset:         246
        .size:           2
        .value_kind:     hidden_group_size_y
      - .offset:         248
        .size:           2
        .value_kind:     hidden_group_size_z
      - .offset:         250
        .size:           2
        .value_kind:     hidden_remainder_x
      - .offset:         252
        .size:           2
        .value_kind:     hidden_remainder_y
      - .offset:         254
        .size:           2
        .value_kind:     hidden_remainder_z
      - .offset:         272
        .size:           8
        .value_kind:     hidden_global_offset_x
      - .offset:         280
        .size:           8
        .value_kind:     hidden_global_offset_y
      - .offset:         288
        .size:           8
        .value_kind:     hidden_global_offset_z
      - .offset:         296
        .size:           2
        .value_kind:     hidden_grid_dims
      - .offset:         352
        .size:           4
        .value_kind:     hidden_dynamic_lds_size
    .group_segment_fixed_size: 0
    .kernarg_segment_align: 8
    .kernarg_segment_size: 488
    .language:       OpenCL C
    .language_version:
      - 2
      - 0
    .max_flat_workgroup_size: 512
    .name:           _Z10fwd_kernelILi13ELi14EEv4Args
    .private_segment_fixed_size: 0
    .sgpr_count:     67
    .sgpr_spill_count: 0
    .symbol:         _Z10fwd_kernelILi13ELi14EEv4Args.kd
    .uniform_work_group_size: 1
    .uses_dynamic_stack: false
    .vgpr_count:     240
    .vgpr_spill_count: 0
    .wavefront_size: 64
  - .agpr_count:     0
    .args:
      - .offset:         0
        .size:           232
        .value_kind:     by_value
      - .offset:         232
        .size:           4
        .value_kind:     hidden_block_count_x
      - .offset:         236
        .size:           4
        .value_kind:     hidden_block_count_y
      - .offset:         240
        .size:           4
        .value_kind:     hidden_block_count_z
      - .offset:         244
        .size:           2
        .value_kind:     hidden_group_size_x
      - .offset:         246
        .size:           2
        .value_kind:     hidden_group_size_y
      - .offset:         248
        .size:           2
        .value_kind:     hidden_group_size_z
      - .offset:         250
        .size:           2
        .value_kind:     hidden_remainder_x
      - .offset:         252
        .size:           2
        .value_kind:     hidden_remainder_y
      - .offset:         254
        .size:           2
        .value_kind:     hidden_remainder_z
      - .offset:         272
        .size:           8
        .value_kind:     hidden_global_offset_x
      - .offset:         280
        .size:           8
        .value_kind:     hidden_global_offset_y
      - .offset:         288
        .size:           8
        .value_kind:     hidden_global_offset_z
      - .offset:         296
        .size:           2
        .value_kind:     hidden_grid_dims
    .group_segment_fixed_size: 0
    .kernarg_segment_align: 8
    .kernarg_segment_size: 488
    .language:       OpenCL C
    .language_version:
      - 2
      - 0
    .max_flat_workgroup_size: 512
    .name:           _Z10fwd_kernelILi14ELi15EEv4Args
    .private_segment_fixed_size: 0
    .sgpr_count:     62
    .sgpr_spill_count: 0
    .symbol:         _Z10fwd_kernelILi14ELi15EEv4Args.kd
    .uniform_work_group_size: 1
    .uses_dynamic_stack: false
    .vgpr_count:     208
    .vgpr_spill_count: 0
    .wavefront_size: 64
